# v088 + hand-written GEMV loop + batched silu(c) staging + one-call 3-unit early GEMV on retention workgroups + batched census loads
# speedup vs baseline: 1.0052x; 1.0037x over previous
.LBB0_17:
	s_and_b64 vcc, exec, s[46:47]
	s_cbranch_vccnz .LBB0_33
	s_and_saveexec_b64 s[50:51], s[38:39]
	s_cbranch_execz .LBB0_32
	v_lshlrev_b32_e32 v32, 2, v8
	v_mov_b32_e32 v34, v32
	v_add_u32_e32 v35, 0x10000, v32
	global_load_dword v24, v32, s[8:9]
	v_add_u32_e32 v33, 0x800, v32
	global_load_dword v25, v33, s[8:9]
	v_add_u32_e32 v33, 0x1000, v32
	global_load_dword v26, v33, s[8:9]
	v_add_u32_e32 v33, 0x1800, v32
	global_load_dword v27, v33, s[8:9]
	v_add_u32_e32 v33, 0x2000, v32
	global_load_dword v28, v33, s[8:9]
	v_add_u32_e32 v33, 0x2800, v32
	global_load_dword v29, v33, s[8:9]
	v_add_u32_e32 v33, 0x3000, v32
	global_load_dword v30, v33, s[8:9]
	v_add_u32_e32 v33, 0x3800, v32
	global_load_dword v31, v33, s[8:9]
	s_waitcnt vmcnt(7)
	v_mov_b32_e32 v10, v24
	v_mul_f32_e32 v11, 0xbfb8aa3b, v10
	v_rndne_f32_e32 v14, v11
	v_fma_f32 v15, v10, s17, -v11
	v_sub_f32_e32 v11, v11, v14
	v_fmac_f32_e32 v15, 0xb2a5705f, v10
	v_add_f32_e32 v11, v11, v15
	v_cvt_i32_f32_e32 v14, v14
	v_exp_f32_e32 v11, v11
	v_cmp_nlt_f32_e64 s[46:47], s18, v10
	s_nop 0
	v_ldexp_f32 v11, v11, v14
	v_cndmask_b32_e64 v11, 0, v11, s[46:47]
	v_cmp_ngt_f32_e64 s[46:47], s19, v10
	s_nop 1
	v_cndmask_b32_e64 v11, v205, v11, s[46:47]
	v_add_f32_e32 v11, 1.0, v11
	v_div_scale_f32 v12, s[46:47], v11, v11, v10
	v_rcp_f32_e32 v14, v12
	v_div_scale_f32 v21, vcc, v10, v11, v10
	v_fma_f32 v22, -v12, v14, 1.0
	v_fmac_f32_e32 v14, v22, v14
	v_mul_f32_e32 v22, v21, v14
	v_fma_f32 v23, -v12, v22, v21
	v_fmac_f32_e32 v22, v23, v14
	v_fma_f32 v12, -v12, v22, v21
	v_div_fmas_f32 v12, v12, v14, v22
	v_div_fixup_f32 v10, v12, v11, v10
	ds_write_b32 v34, v10
	s_waitcnt vmcnt(6)
	v_mov_b32_e32 v10, v25
	v_mul_f32_e32 v11, 0xbfb8aa3b, v10
	v_rndne_f32_e32 v14, v11
	v_fma_f32 v15, v10, s17, -v11
	v_sub_f32_e32 v11, v11, v14
	v_fmac_f32_e32 v15, 0xb2a5705f, v10
	v_add_f32_e32 v11, v11, v15
	v_cvt_i32_f32_e32 v14, v14
	v_exp_f32_e32 v11, v11
	v_cmp_nlt_f32_e64 s[46:47], s18, v10
	s_nop 0
	v_ldexp_f32 v11, v11, v14
	v_cndmask_b32_e64 v11, 0, v11, s[46:47]
	v_cmp_ngt_f32_e64 s[46:47], s19, v10
	s_nop 1
	v_cndmask_b32_e64 v11, v205, v11, s[46:47]
	v_add_f32_e32 v11, 1.0, v11
	v_div_scale_f32 v12, s[46:47], v11, v11, v10
	v_rcp_f32_e32 v14, v12
	v_div_scale_f32 v21, vcc, v10, v11, v10
	v_fma_f32 v22, -v12, v14, 1.0
	v_fmac_f32_e32 v14, v22, v14
	v_mul_f32_e32 v22, v21, v14
	v_fma_f32 v23, -v12, v22, v21
	v_fmac_f32_e32 v22, v23, v14
	v_fma_f32 v12, -v12, v22, v21
	v_div_fmas_f32 v12, v12, v14, v22
	v_div_fixup_f32 v10, v12, v11, v10
	ds_write_b32 v34, v10 offset:2048
	s_waitcnt vmcnt(5)
	v_mov_b32_e32 v10, v26
	v_mul_f32_e32 v11, 0xbfb8aa3b, v10
	v_rndne_f32_e32 v14, v11
	v_fma_f32 v15, v10, s17, -v11
	v_sub_f32_e32 v11, v11, v14
	v_fmac_f32_e32 v15, 0xb2a5705f, v10
	v_add_f32_e32 v11, v11, v15
	v_cvt_i32_f32_e32 v14, v14
	v_exp_f32_e32 v11, v11
	v_cmp_nlt_f32_e64 s[46:47], s18, v10
	s_nop 0
	v_ldexp_f32 v11, v11, v14
	v_cndmask_b32_e64 v11, 0, v11, s[46:47]
	v_cmp_ngt_f32_e64 s[46:47], s19, v10
	s_nop 1
	v_cndmask_b32_e64 v11, v205, v11, s[46:47]
	v_add_f32_e32 v11, 1.0, v11
	v_div_scale_f32 v12, s[46:47], v11, v11, v10
	v_rcp_f32_e32 v14, v12
	v_div_scale_f32 v21, vcc, v10, v11, v10
	v_fma_f32 v22, -v12, v14, 1.0
	v_fmac_f32_e32 v14, v22, v14
	v_mul_f32_e32 v22, v21, v14
	v_fma_f32 v23, -v12, v22, v21
	v_fmac_f32_e32 v22, v23, v14
	v_fma_f32 v12, -v12, v22, v21
	v_div_fmas_f32 v12, v12, v14, v22
	v_div_fixup_f32 v10, v12, v11, v10
	ds_write_b32 v34, v10 offset:4096
	s_waitcnt vmcnt(4)
	v_mov_b32_e32 v10, v27
	v_mul_f32_e32 v11, 0xbfb8aa3b, v10
	v_rndne_f32_e32 v14, v11
	v_fma_f32 v15, v10, s17, -v11
	v_sub_f32_e32 v11, v11, v14
	v_fmac_f32_e32 v15, 0xb2a5705f, v10
	v_add_f32_e32 v11, v11, v15
	v_cvt_i32_f32_e32 v14, v14
	v_exp_f32_e32 v11, v11
	v_cmp_nlt_f32_e64 s[46:47], s18, v10
	s_nop 0
	v_ldexp_f32 v11, v11, v14
	v_cndmask_b32_e64 v11, 0, v11, s[46:47]
	v_cmp_ngt_f32_e64 s[46:47], s19, v10
	s_nop 1
	v_cndmask_b32_e64 v11, v205, v11, s[46:47]
	v_add_f32_e32 v11, 1.0, v11
	v_div_scale_f32 v12, s[46:47], v11, v11, v10
	v_rcp_f32_e32 v14, v12
	v_div_scale_f32 v21, vcc, v10, v11, v10
	v_fma_f32 v22, -v12, v14, 1.0
	v_fmac_f32_e32 v14, v22, v14
	v_mul_f32_e32 v22, v21, v14
	v_fma_f32 v23, -v12, v22, v21
	v_fmac_f32_e32 v22, v23, v14
	v_fma_f32 v12, -v12, v22, v21
	v_div_fmas_f32 v12, v12, v14, v22
	v_div_fixup_f32 v10, v12, v11, v10
	ds_write_b32 v34, v10 offset:6144
	s_waitcnt vmcnt(3)
	v_mov_b32_e32 v10, v28
	v_mul_f32_e32 v11, 0xbfb8aa3b, v10
	v_rndne_f32_e32 v14, v11
	v_fma_f32 v15, v10, s17, -v11
	v_sub_f32_e32 v11, v11, v14
	v_fmac_f32_e32 v15, 0xb2a5705f, v10
	v_add_f32_e32 v11, v11, v15
	v_cvt_i32_f32_e32 v14, v14
	v_exp_f32_e32 v11, v11
	v_cmp_nlt_f32_e64 s[46:47], s18, v10
	s_nop 0
	v_ldexp_f32 v11, v11, v14
	v_cndmask_b32_e64 v11, 0, v11, s[46:47]
	v_cmp_ngt_f32_e64 s[46:47], s19, v10
	s_nop 1
	v_cndmask_b32_e64 v11, v205, v11, s[46:47]
	v_add_f32_e32 v11, 1.0, v11
	v_div_scale_f32 v12, s[46:47], v11, v11, v10
	v_rcp_f32_e32 v14, v12
	v_div_scale_f32 v21, vcc, v10, v11, v10
	v_fma_f32 v22, -v12, v14, 1.0
	v_fmac_f32_e32 v14, v22, v14
	v_mul_f32_e32 v22, v21, v14
	v_fma_f32 v23, -v12, v22, v21
	v_fmac_f32_e32 v22, v23, v14
	v_fma_f32 v12, -v12, v22, v21
	v_div_fmas_f32 v12, v12, v14, v22
	v_div_fixup_f32 v10, v12, v11, v10
	ds_write_b32 v34, v10 offset:8192
	s_waitcnt vmcnt(2)
	v_mov_b32_e32 v10, v29
	v_mul_f32_e32 v11, 0xbfb8aa3b, v10
	v_rndne_f32_e32 v14, v11
	v_fma_f32 v15, v10, s17, -v11
	v_sub_f32_e32 v11, v11, v14
	v_fmac_f32_e32 v15, 0xb2a5705f, v10
	v_add_f32_e32 v11, v11, v15
	v_cvt_i32_f32_e32 v14, v14
	v_exp_f32_e32 v11, v11
	v_cmp_nlt_f32_e64 s[46:47], s18, v10
	s_nop 0
	v_ldexp_f32 v11, v11, v14
	v_cndmask_b32_e64 v11, 0, v11, s[46:47]
	v_cmp_ngt_f32_e64 s[46:47], s19, v10
	s_nop 1
	v_cndmask_b32_e64 v11, v205, v11, s[46:47]
	v_add_f32_e32 v11, 1.0, v11
	v_div_scale_f32 v12, s[46:47], v11, v11, v10
	v_rcp_f32_e32 v14, v12
	v_div_scale_f32 v21, vcc, v10, v11, v10
	v_fma_f32 v22, -v12, v14, 1.0
	v_fmac_f32_e32 v14, v22, v14
	v_mul_f32_e32 v22, v21, v14
	v_fma_f32 v23, -v12, v22, v21
	v_fmac_f32_e32 v22, v23, v14
	v_fma_f32 v12, -v12, v22, v21
	v_div_fmas_f32 v12, v12, v14, v22
	v_div_fixup_f32 v10, v12, v11, v10
	ds_write_b32 v34, v10 offset:10240
	s_waitcnt vmcnt(1)
	v_mov_b32_e32 v10, v30
	v_mul_f32_e32 v11, 0xbfb8aa3b, v10
	v_rndne_f32_e32 v14, v11
	v_fma_f32 v15, v10, s17, -v11
	v_sub_f32_e32 v11, v11, v14
	v_fmac_f32_e32 v15, 0xb2a5705f, v10
	v_add_f32_e32 v11, v11, v15
	v_cvt_i32_f32_e32 v14, v14
	v_exp_f32_e32 v11, v11
	v_cmp_nlt_f32_e64 s[46:47], s18, v10
	s_nop 0
	v_ldexp_f32 v11, v11, v14
	v_cndmask_b32_e64 v11, 0, v11, s[46:47]
	v_cmp_ngt_f32_e64 s[46:47], s19, v10
	s_nop 1
	v_cndmask_b32_e64 v11, v205, v11, s[46:47]
	v_add_f32_e32 v11, 1.0, v11
	v_div_scale_f32 v12, s[46:47], v11, v11, v10
	v_rcp_f32_e32 v14, v12
	v_div_scale_f32 v21, vcc, v10, v11, v10
	v_fma_f32 v22, -v12, v14, 1.0
	v_fmac_f32_e32 v14, v22, v14
	v_mul_f32_e32 v22, v21, v14
	v_fma_f32 v23, -v12, v22, v21
	v_fmac_f32_e32 v22, v23, v14
	v_fma_f32 v12, -v12, v22, v21
	v_div_fmas_f32 v12, v12, v14, v22
	v_div_fixup_f32 v10, v12, v11, v10
	ds_write_b32 v34, v10 offset:12288
	s_waitcnt vmcnt(0)
	v_mov_b32_e32 v10, v31
	v_mul_f32_e32 v11, 0xbfb8aa3b, v10
	v_rndne_f32_e32 v14, v11
	v_fma_f32 v15, v10, s17, -v11
	v_sub_f32_e32 v11, v11, v14
	v_fmac_f32_e32 v15, 0xb2a5705f, v10
	v_add_f32_e32 v11, v11, v15
	v_cvt_i32_f32_e32 v14, v14
	v_exp_f32_e32 v11, v11
	v_cmp_nlt_f32_e64 s[46:47], s18, v10
	s_nop 0
	v_ldexp_f32 v11, v11, v14
	v_cndmask_b32_e64 v11, 0, v11, s[46:47]
	v_cmp_ngt_f32_e64 s[46:47], s19, v10
	s_nop 1
	v_cndmask_b32_e64 v11, v205, v11, s[46:47]
	v_add_f32_e32 v11, 1.0, v11
	v_div_scale_f32 v12, s[46:47], v11, v11, v10
	v_rcp_f32_e32 v14, v12
	v_div_scale_f32 v21, vcc, v10, v11, v10
	v_fma_f32 v22, -v12, v14, 1.0
	v_fmac_f32_e32 v14, v22, v14
	v_mul_f32_e32 v22, v21, v14
	v_fma_f32 v23, -v12, v22, v21
	v_fmac_f32_e32 v22, v23, v14
	v_fma_f32 v12, -v12, v22, v21
	v_div_fmas_f32 v12, v12, v14, v22
	v_div_fixup_f32 v10, v12, v11, v10
	ds_write_b32 v34, v10 offset:14336
	v_add_u32_e32 v33, 0x4000, v32
	global_load_dword v24, v33, s[8:9]
	v_add_u32_e32 v33, 0x4800, v32
	global_load_dword v25, v33, s[8:9]
	v_add_u32_e32 v33, 0x5000, v32
	global_load_dword v26, v33, s[8:9]
	v_add_u32_e32 v33, 0x5800, v32
	global_load_dword v27, v33, s[8:9]
	v_add_u32_e32 v33, 0x6000, v32
	global_load_dword v28, v33, s[8:9]
	v_add_u32_e32 v33, 0x6800, v32
	global_load_dword v29, v33, s[8:9]
	v_add_u32_e32 v33, 0x7000, v32
	global_load_dword v30, v33, s[8:9]
	v_add_u32_e32 v33, 0x7800, v32
	global_load_dword v31, v33, s[8:9]
	s_waitcnt vmcnt(7)
	v_mov_b32_e32 v10, v24
	v_mul_f32_e32 v11, 0xbfb8aa3b, v10
	v_rndne_f32_e32 v14, v11
	v_fma_f32 v15, v10, s17, -v11
	v_sub_f32_e32 v11, v11, v14
	v_fmac_f32_e32 v15, 0xb2a5705f, v10
	v_add_f32_e32 v11, v11, v15
	v_cvt_i32_f32_e32 v14, v14
	v_exp_f32_e32 v11, v11
	v_cmp_nlt_f32_e64 s[46:47], s18, v10
	s_nop 0
	v_ldexp_f32 v11, v11, v14
	v_cndmask_b32_e64 v11, 0, v11, s[46:47]
	v_cmp_ngt_f32_e64 s[46:47], s19, v10
	s_nop 1
	v_cndmask_b32_e64 v11, v205, v11, s[46:47]
	v_add_f32_e32 v11, 1.0, v11
	v_div_scale_f32 v12, s[46:47], v11, v11, v10
	v_rcp_f32_e32 v14, v12
	v_div_scale_f32 v21, vcc, v10, v11, v10
	v_fma_f32 v22, -v12, v14, 1.0
	v_fmac_f32_e32 v14, v22, v14
	v_mul_f32_e32 v22, v21, v14
	v_fma_f32 v23, -v12, v22, v21
	v_fmac_f32_e32 v22, v23, v14
	v_fma_f32 v12, -v12, v22, v21
	v_div_fmas_f32 v12, v12, v14, v22
	v_div_fixup_f32 v10, v12, v11, v10
	ds_write_b32 v34, v10 offset:16384
	s_waitcnt vmcnt(6)
	v_mov_b32_e32 v10, v25
	v_mul_f32_e32 v11, 0xbfb8aa3b, v10
	v_rndne_f32_e32 v14, v11
	v_fma_f32 v15, v10, s17, -v11
	v_sub_f32_e32 v11, v11, v14
	v_fmac_f32_e32 v15, 0xb2a5705f, v10
	v_add_f32_e32 v11, v11, v15
	v_cvt_i32_f32_e32 v14, v14
	v_exp_f32_e32 v11, v11
	v_cmp_nlt_f32_e64 s[46:47], s18, v10
	s_nop 0
	v_ldexp_f32 v11, v11, v14
	v_cndmask_b32_e64 v11, 0, v11, s[46:47]
	v_cmp_ngt_f32_e64 s[46:47], s19, v10
	s_nop 1
	v_cndmask_b32_e64 v11, v205, v11, s[46:47]
	v_add_f32_e32 v11, 1.0, v11
	v_div_scale_f32 v12, s[46:47], v11, v11, v10
	v_rcp_f32_e32 v14, v12
	v_div_scale_f32 v21, vcc, v10, v11, v10
	v_fma_f32 v22, -v12, v14, 1.0
	v_fmac_f32_e32 v14, v22, v14
	v_mul_f32_e32 v22, v21, v14
	v_fma_f32 v23, -v12, v22, v21
	v_fmac_f32_e32 v22, v23, v14
	v_fma_f32 v12, -v12, v22, v21
	v_div_fmas_f32 v12, v12, v14, v22
	v_div_fixup_f32 v10, v12, v11, v10
	ds_write_b32 v34, v10 offset:18432
	s_waitcnt vmcnt(5)
	v_mov_b32_e32 v10, v26
	v_mul_f32_e32 v11, 0xbfb8aa3b, v10
	v_rndne_f32_e32 v14, v11
	v_fma_f32 v15, v10, s17, -v11
	v_sub_f32_e32 v11, v11, v14
	v_fmac_f32_e32 v15, 0xb2a5705f, v10
	v_add_f32_e32 v11, v11, v15
	v_cvt_i32_f32_e32 v14, v14
	v_exp_f32_e32 v11, v11
	v_cmp_nlt_f32_e64 s[46:47], s18, v10
	s_nop 0
	v_ldexp_f32 v11, v11, v14
	v_cndmask_b32_e64 v11, 0, v11, s[46:47]
	v_cmp_ngt_f32_e64 s[46:47], s19, v10
	s_nop 1
	v_cndmask_b32_e64 v11, v205, v11, s[46:47]
	v_add_f32_e32 v11, 1.0, v11
	v_div_scale_f32 v12, s[46:47], v11, v11, v10
	v_rcp_f32_e32 v14, v12
	v_div_scale_f32 v21, vcc, v10, v11, v10
	v_fma_f32 v22, -v12, v14, 1.0
	v_fmac_f32_e32 v14, v22, v14
	v_mul_f32_e32 v22, v21, v14
	v_fma_f32 v23, -v12, v22, v21
	v_fmac_f32_e32 v22, v23, v14
	v_fma_f32 v12, -v12, v22, v21
	v_div_fmas_f32 v12, v12, v14, v22
	v_div_fixup_f32 v10, v12, v11, v10
	ds_write_b32 v34, v10 offset:20480
	s_waitcnt vmcnt(4)
	v_mov_b32_e32 v10, v27
	v_mul_f32_e32 v11, 0xbfb8aa3b, v10
	v_rndne_f32_e32 v14, v11
	v_fma_f32 v15, v10, s17, -v11
	v_sub_f32_e32 v11, v11, v14
	v_fmac_f32_e32 v15, 0xb2a5705f, v10
	v_add_f32_e32 v11, v11, v15
	v_cvt_i32_f32_e32 v14, v14
	v_exp_f32_e32 v11, v11
	v_cmp_nlt_f32_e64 s[46:47], s18, v10
	s_nop 0
	v_ldexp_f32 v11, v11, v14
	v_cndmask_b32_e64 v11, 0, v11, s[46:47]
	v_cmp_ngt_f32_e64 s[46:47], s19, v10
	s_nop 1
	v_cndmask_b32_e64 v11, v205, v11, s[46:47]
	v_add_f32_e32 v11, 1.0, v11
	v_div_scale_f32 v12, s[46:47], v11, v11, v10
	v_rcp_f32_e32 v14, v12
	v_div_scale_f32 v21, vcc, v10, v11, v10
	v_fma_f32 v22, -v12, v14, 1.0
	v_fmac_f32_e32 v14, v22, v14
	v_mul_f32_e32 v22, v21, v14
	v_fma_f32 v23, -v12, v22, v21
	v_fmac_f32_e32 v22, v23, v14
	v_fma_f32 v12, -v12, v22, v21
	v_div_fmas_f32 v12, v12, v14, v22
	v_div_fixup_f32 v10, v12, v11, v10
	ds_write_b32 v34, v10 offset:22528
	s_waitcnt vmcnt(3)
	v_mov_b32_e32 v10, v28
	v_mul_f32_e32 v11, 0xbfb8aa3b, v10
	v_rndne_f32_e32 v14, v11
	v_fma_f32 v15, v10, s17, -v11
	v_sub_f32_e32 v11, v11, v14
	v_fmac_f32_e32 v15, 0xb2a5705f, v10
	v_add_f32_e32 v11, v11, v15
	v_cvt_i32_f32_e32 v14, v14
	v_exp_f32_e32 v11, v11
	v_cmp_nlt_f32_e64 s[46:47], s18, v10
	s_nop 0
	v_ldexp_f32 v11, v11, v14
	v_cndmask_b32_e64 v11, 0, v11, s[46:47]
	v_cmp_ngt_f32_e64 s[46:47], s19, v10
	s_nop 1
	v_cndmask_b32_e64 v11, v205, v11, s[46:47]
	v_add_f32_e32 v11, 1.0, v11
	v_div_scale_f32 v12, s[46:47], v11, v11, v10
	v_rcp_f32_e32 v14, v12
	v_div_scale_f32 v21, vcc, v10, v11, v10
	v_fma_f32 v22, -v12, v14, 1.0
	v_fmac_f32_e32 v14, v22, v14
	v_mul_f32_e32 v22, v21, v14
	v_fma_f32 v23, -v12, v22, v21
	v_fmac_f32_e32 v22, v23, v14
	v_fma_f32 v12, -v12, v22, v21
	v_div_fmas_f32 v12, v12, v14, v22
	v_div_fixup_f32 v10, v12, v11, v10
	ds_write_b32 v34, v10 offset:24576
	s_waitcnt vmcnt(2)
	v_mov_b32_e32 v10, v29
	v_mul_f32_e32 v11, 0xbfb8aa3b, v10
	v_rndne_f32_e32 v14, v11
	v_fma_f32 v15, v10, s17, -v11
	v_sub_f32_e32 v11, v11, v14
	v_fmac_f32_e32 v15, 0xb2a5705f, v10
	v_add_f32_e32 v11, v11, v15
	v_cvt_i32_f32_e32 v14, v14
	v_exp_f32_e32 v11, v11
	v_cmp_nlt_f32_e64 s[46:47], s18, v10
	s_nop 0
	v_ldexp_f32 v11, v11, v14
	v_cndmask_b32_e64 v11, 0, v11, s[46:47]
	v_cmp_ngt_f32_e64 s[46:47], s19, v10
	s_nop 1
	v_cndmask_b32_e64 v11, v205, v11, s[46:47]
	v_add_f32_e32 v11, 1.0, v11
	v_div_scale_f32 v12, s[46:47], v11, v11, v10
	v_rcp_f32_e32 v14, v12
	v_div_scale_f32 v21, vcc, v10, v11, v10
	v_fma_f32 v22, -v12, v14, 1.0
	v_fmac_f32_e32 v14, v22, v14
	v_mul_f32_e32 v22, v21, v14
	v_fma_f32 v23, -v12, v22, v21
	v_fmac_f32_e32 v22, v23, v14
	v_fma_f32 v12, -v12, v22, v21
	v_div_fmas_f32 v12, v12, v14, v22
	v_div_fixup_f32 v10, v12, v11, v10
	ds_write_b32 v34, v10 offset:26624
	s_waitcnt vmcnt(1)
	v_mov_b32_e32 v10, v30
	v_mul_f32_e32 v11, 0xbfb8aa3b, v10
	v_rndne_f32_e32 v14, v11
	v_fma_f32 v15, v10, s17, -v11
	v_sub_f32_e32 v11, v11, v14
	v_fmac_f32_e32 v15, 0xb2a5705f, v10
	v_add_f32_e32 v11, v11, v15
	v_cvt_i32_f32_e32 v14, v14
	v_exp_f32_e32 v11, v11
	v_cmp_nlt_f32_e64 s[46:47], s18, v10
	s_nop 0
	v_ldexp_f32 v11, v11, v14
	v_cndmask_b32_e64 v11, 0, v11, s[46:47]
	v_cmp_ngt_f32_e64 s[46:47], s19, v10
	s_nop 1
	v_cndmask_b32_e64 v11, v205, v11, s[46:47]
	v_add_f32_e32 v11, 1.0, v11
	v_div_scale_f32 v12, s[46:47], v11, v11, v10
	v_rcp_f32_e32 v14, v12
	v_div_scale_f32 v21, vcc, v10, v11, v10
	v_fma_f32 v22, -v12, v14, 1.0
	v_fmac_f32_e32 v14, v22, v14
	v_mul_f32_e32 v22, v21, v14
	v_fma_f32 v23, -v12, v22, v21
	v_fmac_f32_e32 v22, v23, v14
	v_fma_f32 v12, -v12, v22, v21
	v_div_fmas_f32 v12, v12, v14, v22
	v_div_fixup_f32 v10, v12, v11, v10
	ds_write_b32 v34, v10 offset:28672
	s_waitcnt vmcnt(0)
	v_mov_b32_e32 v10, v31
	v_mul_f32_e32 v11, 0xbfb8aa3b, v10
	v_rndne_f32_e32 v14, v11
	v_fma_f32 v15, v10, s17, -v11
	v_sub_f32_e32 v11, v11, v14
	v_fmac_f32_e32 v15, 0xb2a5705f, v10
	v_add_f32_e32 v11, v11, v15
	v_cvt_i32_f32_e32 v14, v14
	v_exp_f32_e32 v11, v11
	v_cmp_nlt_f32_e64 s[46:47], s18, v10
	s_nop 0
	v_ldexp_f32 v11, v11, v14
	v_cndmask_b32_e64 v11, 0, v11, s[46:47]
	v_cmp_ngt_f32_e64 s[46:47], s19, v10
	s_nop 1
	v_cndmask_b32_e64 v11, v205, v11, s[46:47]
	v_add_f32_e32 v11, 1.0, v11
	v_div_scale_f32 v12, s[46:47], v11, v11, v10
	v_rcp_f32_e32 v14, v12
	v_div_scale_f32 v21, vcc, v10, v11, v10
	v_fma_f32 v22, -v12, v14, 1.0
	v_fmac_f32_e32 v14, v22, v14
	v_mul_f32_e32 v22, v21, v14
	v_fma_f32 v23, -v12, v22, v21
	v_fmac_f32_e32 v22, v23, v14
	v_fma_f32 v12, -v12, v22, v21
	v_div_fmas_f32 v12, v12, v14, v22
	v_div_fixup_f32 v10, v12, v11, v10
	ds_write_b32 v34, v10 offset:30720
	v_add_u32_e32 v33, 0x8000, v32
	global_load_dword v24, v33, s[8:9]
	v_add_u32_e32 v33, 0x8800, v32
	global_load_dword v25, v33, s[8:9]
	v_add_u32_e32 v33, 0x9000, v32
	global_load_dword v26, v33, s[8:9]
	v_add_u32_e32 v33, 0x9800, v32
	global_load_dword v27, v33, s[8:9]
	v_add_u32_e32 v33, 0xa000, v32
	global_load_dword v28, v33, s[8:9]
	v_add_u32_e32 v33, 0xa800, v32
	global_load_dword v29, v33, s[8:9]
	v_add_u32_e32 v33, 0xb000, v32
	global_load_dword v30, v33, s[8:9]
	v_add_u32_e32 v33, 0xb800, v32
	global_load_dword v31, v33, s[8:9]
	s_waitcnt vmcnt(7)
	v_mov_b32_e32 v10, v24
	v_mul_f32_e32 v11, 0xbfb8aa3b, v10
	v_rndne_f32_e32 v14, v11
	v_fma_f32 v15, v10, s17, -v11
	v_sub_f32_e32 v11, v11, v14
	v_fmac_f32_e32 v15, 0xb2a5705f, v10
	v_add_f32_e32 v11, v11, v15
	v_cvt_i32_f32_e32 v14, v14
	v_exp_f32_e32 v11, v11
	v_cmp_nlt_f32_e64 s[46:47], s18, v10
	s_nop 0
	v_ldexp_f32 v11, v11, v14
	v_cndmask_b32_e64 v11, 0, v11, s[46:47]
	v_cmp_ngt_f32_e64 s[46:47], s19, v10
	s_nop 1
	v_cndmask_b32_e64 v11, v205, v11, s[46:47]
	v_add_f32_e32 v11, 1.0, v11
	v_div_scale_f32 v12, s[46:47], v11, v11, v10
	v_rcp_f32_e32 v14, v12
	v_div_scale_f32 v21, vcc, v10, v11, v10
	v_fma_f32 v22, -v12, v14, 1.0
	v_fmac_f32_e32 v14, v22, v14
	v_mul_f32_e32 v22, v21, v14
	v_fma_f32 v23, -v12, v22, v21
	v_fmac_f32_e32 v22, v23, v14
	v_fma_f32 v12, -v12, v22, v21
	v_div_fmas_f32 v12, v12, v14, v22
	v_div_fixup_f32 v10, v12, v11, v10
	ds_write_b32 v34, v10 offset:32768
	s_waitcnt vmcnt(6)
	v_mov_b32_e32 v10, v25
	v_mul_f32_e32 v11, 0xbfb8aa3b, v10
	v_rndne_f32_e32 v14, v11
	v_fma_f32 v15, v10, s17, -v11
	v_sub_f32_e32 v11, v11, v14
	v_fmac_f32_e32 v15, 0xb2a5705f, v10
	v_add_f32_e32 v11, v11, v15
	v_cvt_i32_f32_e32 v14, v14
	v_exp_f32_e32 v11, v11
	v_cmp_nlt_f32_e64 s[46:47], s18, v10
	s_nop 0
	v_ldexp_f32 v11, v11, v14
	v_cndmask_b32_e64 v11, 0, v11, s[46:47]
	v_cmp_ngt_f32_e64 s[46:47], s19, v10
	s_nop 1
	v_cndmask_b32_e64 v11, v205, v11, s[46:47]
	v_add_f32_e32 v11, 1.0, v11
	v_div_scale_f32 v12, s[46:47], v11, v11, v10
	v_rcp_f32_e32 v14, v12
	v_div_scale_f32 v21, vcc, v10, v11, v10
	v_fma_f32 v22, -v12, v14, 1.0
	v_fmac_f32_e32 v14, v22, v14
	v_mul_f32_e32 v22, v21, v14
	v_fma_f32 v23, -v12, v22, v21
	v_fmac_f32_e32 v22, v23, v14
	v_fma_f32 v12, -v12, v22, v21
	v_div_fmas_f32 v12, v12, v14, v22
	v_div_fixup_f32 v10, v12, v11, v10
	ds_write_b32 v34, v10 offset:34816
	s_waitcnt vmcnt(5)
	v_mov_b32_e32 v10, v26
	v_mul_f32_e32 v11, 0xbfb8aa3b, v10
	v_rndne_f32_e32 v14, v11
	v_fma_f32 v15, v10, s17, -v11
	v_sub_f32_e32 v11, v11, v14
	v_fmac_f32_e32 v15, 0xb2a5705f, v10
	v_add_f32_e32 v11, v11, v15
	v_cvt_i32_f32_e32 v14, v14
	v_exp_f32_e32 v11, v11
	v_cmp_nlt_f32_e64 s[46:47], s18, v10
	s_nop 0
	v_ldexp_f32 v11, v11, v14
	v_cndmask_b32_e64 v11, 0, v11, s[46:47]
	v_cmp_ngt_f32_e64 s[46:47], s19, v10
	s_nop 1
	v_cndmask_b32_e64 v11, v205, v11, s[46:47]
	v_add_f32_e32 v11, 1.0, v11
	v_div_scale_f32 v12, s[46:47], v11, v11, v10
	v_rcp_f32_e32 v14, v12
	v_div_scale_f32 v21, vcc, v10, v11, v10
	v_fma_f32 v22, -v12, v14, 1.0
	v_fmac_f32_e32 v14, v22, v14
	v_mul_f32_e32 v22, v21, v14
	v_fma_f32 v23, -v12, v22, v21
	v_fmac_f32_e32 v22, v23, v14
	v_fma_f32 v12, -v12, v22, v21
	v_div_fmas_f32 v12, v12, v14, v22
	v_div_fixup_f32 v10, v12, v11, v10
	ds_write_b32 v34, v10 offset:36864
	s_waitcnt vmcnt(4)
	v_mov_b32_e32 v10, v27
	v_mul_f32_e32 v11, 0xbfb8aa3b, v10
	v_rndne_f32_e32 v14, v11
	v_fma_f32 v15, v10, s17, -v11
	v_sub_f32_e32 v11, v11, v14
	v_fmac_f32_e32 v15, 0xb2a5705f, v10
	v_add_f32_e32 v11, v11, v15
	v_cvt_i32_f32_e32 v14, v14
	v_exp_f32_e32 v11, v11
	v_cmp_nlt_f32_e64 s[46:47], s18, v10
	s_nop 0
	v_ldexp_f32 v11, v11, v14
	v_cndmask_b32_e64 v11, 0, v11, s[46:47]
	v_cmp_ngt_f32_e64 s[46:47], s19, v10
	s_nop 1
	v_cndmask_b32_e64 v11, v205, v11, s[46:47]
	v_add_f32_e32 v11, 1.0, v11
	v_div_scale_f32 v12, s[46:47], v11, v11, v10
	v_rcp_f32_e32 v14, v12
	v_div_scale_f32 v21, vcc, v10, v11, v10
	v_fma_f32 v22, -v12, v14, 1.0
	v_fmac_f32_e32 v14, v22, v14
	v_mul_f32_e32 v22, v21, v14
	v_fma_f32 v23, -v12, v22, v21
	v_fmac_f32_e32 v22, v23, v14
	v_fma_f32 v12, -v12, v22, v21
	v_div_fmas_f32 v12, v12, v14, v22
	v_div_fixup_f32 v10, v12, v11, v10
	ds_write_b32 v34, v10 offset:38912
	s_waitcnt vmcnt(3)
	v_mov_b32_e32 v10, v28
	v_mul_f32_e32 v11, 0xbfb8aa3b, v10
	v_rndne_f32_e32 v14, v11
	v_fma_f32 v15, v10, s17, -v11
	v_sub_f32_e32 v11, v11, v14
	v_fmac_f32_e32 v15, 0xb2a5705f, v10
	v_add_f32_e32 v11, v11, v15
	v_cvt_i32_f32_e32 v14, v14
	v_exp_f32_e32 v11, v11
	v_cmp_nlt_f32_e64 s[46:47], s18, v10
	s_nop 0
	v_ldexp_f32 v11, v11, v14
	v_cndmask_b32_e64 v11, 0, v11, s[46:47]
	v_cmp_ngt_f32_e64 s[46:47], s19, v10
	s_nop 1
	v_cndmask_b32_e64 v11, v205, v11, s[46:47]
	v_add_f32_e32 v11, 1.0, v11
	v_div_scale_f32 v12, s[46:47], v11, v11, v10
	v_rcp_f32_e32 v14, v12
	v_div_scale_f32 v21, vcc, v10, v11, v10
	v_fma_f32 v22, -v12, v14, 1.0
	v_fmac_f32_e32 v14, v22, v14
	v_mul_f32_e32 v22, v21, v14
	v_fma_f32 v23, -v12, v22, v21
	v_fmac_f32_e32 v22, v23, v14
	v_fma_f32 v12, -v12, v22, v21
	v_div_fmas_f32 v12, v12, v14, v22
	v_div_fixup_f32 v10, v12, v11, v10
	ds_write_b32 v34, v10 offset:40960
	s_waitcnt vmcnt(2)
	v_mov_b32_e32 v10, v29
	v_mul_f32_e32 v11, 0xbfb8aa3b, v10
	v_rndne_f32_e32 v14, v11
	v_fma_f32 v15, v10, s17, -v11
	v_sub_f32_e32 v11, v11, v14
	v_fmac_f32_e32 v15, 0xb2a5705f, v10
	v_add_f32_e32 v11, v11, v15
	v_cvt_i32_f32_e32 v14, v14
	v_exp_f32_e32 v11, v11
	v_cmp_nlt_f32_e64 s[46:47], s18, v10
	s_nop 0
	v_ldexp_f32 v11, v11, v14
	v_cndmask_b32_e64 v11, 0, v11, s[46:47]
	v_cmp_ngt_f32_e64 s[46:47], s19, v10
	s_nop 1
	v_cndmask_b32_e64 v11, v205, v11, s[46:47]
	v_add_f32_e32 v11, 1.0, v11
	v_div_scale_f32 v12, s[46:47], v11, v11, v10
	v_rcp_f32_e32 v14, v12
	v_div_scale_f32 v21, vcc, v10, v11, v10
	v_fma_f32 v22, -v12, v14, 1.0
	v_fmac_f32_e32 v14, v22, v14
	v_mul_f32_e32 v22, v21, v14
	v_fma_f32 v23, -v12, v22, v21
	v_fmac_f32_e32 v22, v23, v14
	v_fma_f32 v12, -v12, v22, v21
	v_div_fmas_f32 v12, v12, v14, v22
	v_div_fixup_f32 v10, v12, v11, v10
	ds_write_b32 v34, v10 offset:43008
	s_waitcnt vmcnt(1)
	v_mov_b32_e32 v10, v30
	v_mul_f32_e32 v11, 0xbfb8aa3b, v10
	v_rndne_f32_e32 v14, v11
	v_fma_f32 v15, v10, s17, -v11
	v_sub_f32_e32 v11, v11, v14
	v_fmac_f32_e32 v15, 0xb2a5705f, v10
	v_add_f32_e32 v11, v11, v15
	v_cvt_i32_f32_e32 v14, v14
	v_exp_f32_e32 v11, v11
	v_cmp_nlt_f32_e64 s[46:47], s18, v10
	s_nop 0
	v_ldexp_f32 v11, v11, v14
	v_cndmask_b32_e64 v11, 0, v11, s[46:47]
	v_cmp_ngt_f32_e64 s[46:47], s19, v10
	s_nop 1
	v_cndmask_b32_e64 v11, v205, v11, s[46:47]
	v_add_f32_e32 v11, 1.0, v11
	v_div_scale_f32 v12, s[46:47], v11, v11, v10
	v_rcp_f32_e32 v14, v12
	v_div_scale_f32 v21, vcc, v10, v11, v10
	v_fma_f32 v22, -v12, v14, 1.0
	v_fmac_f32_e32 v14, v22, v14
	v_mul_f32_e32 v22, v21, v14
	v_fma_f32 v23, -v12, v22, v21
	v_fmac_f32_e32 v22, v23, v14
	v_fma_f32 v12, -v12, v22, v21
	v_div_fmas_f32 v12, v12, v14, v22
	v_div_fixup_f32 v10, v12, v11, v10
	ds_write_b32 v34, v10 offset:45056
	s_waitcnt vmcnt(0)
	v_mov_b32_e32 v10, v31
	v_mul_f32_e32 v11, 0xbfb8aa3b, v10
	v_rndne_f32_e32 v14, v11
	v_fma_f32 v15, v10, s17, -v11
	v_sub_f32_e32 v11, v11, v14
	v_fmac_f32_e32 v15, 0xb2a5705f, v10
	v_add_f32_e32 v11, v11, v15
	v_cvt_i32_f32_e32 v14, v14
	v_exp_f32_e32 v11, v11
	v_cmp_nlt_f32_e64 s[46:47], s18, v10
	s_nop 0
	v_ldexp_f32 v11, v11, v14
	v_cndmask_b32_e64 v11, 0, v11, s[46:47]
	v_cmp_ngt_f32_e64 s[46:47], s19, v10
	s_nop 1
	v_cndmask_b32_e64 v11, v205, v11, s[46:47]
	v_add_f32_e32 v11, 1.0, v11
	v_div_scale_f32 v12, s[46:47], v11, v11, v10
	v_rcp_f32_e32 v14, v12
	v_div_scale_f32 v21, vcc, v10, v11, v10
	v_fma_f32 v22, -v12, v14, 1.0
	v_fmac_f32_e32 v14, v22, v14
	v_mul_f32_e32 v22, v21, v14
	v_fma_f32 v23, -v12, v22, v21
	v_fmac_f32_e32 v22, v23, v14
	v_fma_f32 v12, -v12, v22, v21
	v_div_fmas_f32 v12, v12, v14, v22
	v_div_fixup_f32 v10, v12, v11, v10
	ds_write_b32 v34, v10 offset:47104
	v_add_u32_e32 v33, 0xc000, v32
	global_load_dword v24, v33, s[8:9]
	v_add_u32_e32 v33, 0xc800, v32
	global_load_dword v25, v33, s[8:9]
	v_add_u32_e32 v33, 0xd000, v32
	global_load_dword v26, v33, s[8:9]
	v_add_u32_e32 v33, 0xd800, v32
	global_load_dword v27, v33, s[8:9]
	v_add_u32_e32 v33, 0xe000, v32
	global_load_dword v28, v33, s[8:9]
	v_add_u32_e32 v33, 0xe800, v32
	global_load_dword v29, v33, s[8:9]
	v_add_u32_e32 v33, 0xf000, v32
	global_load_dword v30, v33, s[8:9]
	v_add_u32_e32 v33, 0xf800, v32
	global_load_dword v31, v33, s[8:9]
	s_waitcnt vmcnt(7)
	v_mov_b32_e32 v10, v24
	v_mul_f32_e32 v11, 0xbfb8aa3b, v10
	v_rndne_f32_e32 v14, v11
	v_fma_f32 v15, v10, s17, -v11
	v_sub_f32_e32 v11, v11, v14
	v_fmac_f32_e32 v15, 0xb2a5705f, v10
	v_add_f32_e32 v11, v11, v15
	v_cvt_i32_f32_e32 v14, v14
	v_exp_f32_e32 v11, v11
	v_cmp_nlt_f32_e64 s[46:47], s18, v10
	s_nop 0
	v_ldexp_f32 v11, v11, v14
	v_cndmask_b32_e64 v11, 0, v11, s[46:47]
	v_cmp_ngt_f32_e64 s[46:47], s19, v10
	s_nop 1
	v_cndmask_b32_e64 v11, v205, v11, s[46:47]
	v_add_f32_e32 v11, 1.0, v11
	v_div_scale_f32 v12, s[46:47], v11, v11, v10
	v_rcp_f32_e32 v14, v12
	v_div_scale_f32 v21, vcc, v10, v11, v10
	v_fma_f32 v22, -v12, v14, 1.0
	v_fmac_f32_e32 v14, v22, v14
	v_mul_f32_e32 v22, v21, v14
	v_fma_f32 v23, -v12, v22, v21
	v_fmac_f32_e32 v22, v23, v14
	v_fma_f32 v12, -v12, v22, v21
	v_div_fmas_f32 v12, v12, v14, v22
	v_div_fixup_f32 v10, v12, v11, v10
	ds_write_b32 v34, v10 offset:49152
	s_waitcnt vmcnt(6)
	v_mov_b32_e32 v10, v25
	v_mul_f32_e32 v11, 0xbfb8aa3b, v10
	v_rndne_f32_e32 v14, v11
	v_fma_f32 v15, v10, s17, -v11
	v_sub_f32_e32 v11, v11, v14
	v_fmac_f32_e32 v15, 0xb2a5705f, v10
	v_add_f32_e32 v11, v11, v15
	v_cvt_i32_f32_e32 v14, v14
	v_exp_f32_e32 v11, v11
	v_cmp_nlt_f32_e64 s[46:47], s18, v10
	s_nop 0
	v_ldexp_f32 v11, v11, v14
	v_cndmask_b32_e64 v11, 0, v11, s[46:47]
	v_cmp_ngt_f32_e64 s[46:47], s19, v10
	s_nop 1
	v_cndmask_b32_e64 v11, v205, v11, s[46:47]
	v_add_f32_e32 v11, 1.0, v11
	v_div_scale_f32 v12, s[46:47], v11, v11, v10
	v_rcp_f32_e32 v14, v12
	v_div_scale_f32 v21, vcc, v10, v11, v10
	v_fma_f32 v22, -v12, v14, 1.0
	v_fmac_f32_e32 v14, v22, v14
	v_mul_f32_e32 v22, v21, v14
	v_fma_f32 v23, -v12, v22, v21
	v_fmac_f32_e32 v22, v23, v14
	v_fma_f32 v12, -v12, v22, v21
	v_div_fmas_f32 v12, v12, v14, v22
	v_div_fixup_f32 v10, v12, v11, v10
	ds_write_b32 v34, v10 offset:51200
	s_waitcnt vmcnt(5)
	v_mov_b32_e32 v10, v26
	v_mul_f32_e32 v11, 0xbfb8aa3b, v10
	v_rndne_f32_e32 v14, v11
	v_fma_f32 v15, v10, s17, -v11
	v_sub_f32_e32 v11, v11, v14
	v_fmac_f32_e32 v15, 0xb2a5705f, v10
	v_add_f32_e32 v11, v11, v15
	v_cvt_i32_f32_e32 v14, v14
	v_exp_f32_e32 v11, v11
	v_cmp_nlt_f32_e64 s[46:47], s18, v10
	s_nop 0
	v_ldexp_f32 v11, v11, v14
	v_cndmask_b32_e64 v11, 0, v11, s[46:47]
	v_cmp_ngt_f32_e64 s[46:47], s19, v10
	s_nop 1
	v_cndmask_b32_e64 v11, v205, v11, s[46:47]
	v_add_f32_e32 v11, 1.0, v11
	v_div_scale_f32 v12, s[46:47], v11, v11, v10
	v_rcp_f32_e32 v14, v12
	v_div_scale_f32 v21, vcc, v10, v11, v10
	v_fma_f32 v22, -v12, v14, 1.0
	v_fmac_f32_e32 v14, v22, v14
	v_mul_f32_e32 v22, v21, v14
	v_fma_f32 v23, -v12, v22, v21
	v_fmac_f32_e32 v22, v23, v14
	v_fma_f32 v12, -v12, v22, v21
	v_div_fmas_f32 v12, v12, v14, v22
	v_div_fixup_f32 v10, v12, v11, v10
	ds_write_b32 v34, v10 offset:53248
	s_waitcnt vmcnt(4)
	v_mov_b32_e32 v10, v27
	v_mul_f32_e32 v11, 0xbfb8aa3b, v10
	v_rndne_f32_e32 v14, v11
	v_fma_f32 v15, v10, s17, -v11
	v_sub_f32_e32 v11, v11, v14
	v_fmac_f32_e32 v15, 0xb2a5705f, v10
	v_add_f32_e32 v11, v11, v15
	v_cvt_i32_f32_e32 v14, v14
	v_exp_f32_e32 v11, v11
	v_cmp_nlt_f32_e64 s[46:47], s18, v10
	s_nop 0
	v_ldexp_f32 v11, v11, v14
	v_cndmask_b32_e64 v11, 0, v11, s[46:47]
	v_cmp_ngt_f32_e64 s[46:47], s19, v10
	s_nop 1
	v_cndmask_b32_e64 v11, v205, v11, s[46:47]
	v_add_f32_e32 v11, 1.0, v11
	v_div_scale_f32 v12, s[46:47], v11, v11, v10
	v_rcp_f32_e32 v14, v12
	v_div_scale_f32 v21, vcc, v10, v11, v10
	v_fma_f32 v22, -v12, v14, 1.0
	v_fmac_f32_e32 v14, v22, v14
	v_mul_f32_e32 v22, v21, v14
	v_fma_f32 v23, -v12, v22, v21
	v_fmac_f32_e32 v22, v23, v14
	v_fma_f32 v12, -v12, v22, v21
	v_div_fmas_f32 v12, v12, v14, v22
	v_div_fixup_f32 v10, v12, v11, v10
	ds_write_b32 v34, v10 offset:55296
	s_waitcnt vmcnt(3)
	v_mov_b32_e32 v10, v28
	v_mul_f32_e32 v11, 0xbfb8aa3b, v10
	v_rndne_f32_e32 v14, v11
	v_fma_f32 v15, v10, s17, -v11
	v_sub_f32_e32 v11, v11, v14
	v_fmac_f32_e32 v15, 0xb2a5705f, v10
	v_add_f32_e32 v11, v11, v15
	v_cvt_i32_f32_e32 v14, v14
	v_exp_f32_e32 v11, v11
	v_cmp_nlt_f32_e64 s[46:47], s18, v10
	s_nop 0
	v_ldexp_f32 v11, v11, v14
	v_cndmask_b32_e64 v11, 0, v11, s[46:47]
	v_cmp_ngt_f32_e64 s[46:47], s19, v10
	s_nop 1
	v_cndmask_b32_e64 v11, v205, v11, s[46:47]
	v_add_f32_e32 v11, 1.0, v11
	v_div_scale_f32 v12, s[46:47], v11, v11, v10
	v_rcp_f32_e32 v14, v12
	v_div_scale_f32 v21, vcc, v10, v11, v10
	v_fma_f32 v22, -v12, v14, 1.0
	v_fmac_f32_e32 v14, v22, v14
	v_mul_f32_e32 v22, v21, v14
	v_fma_f32 v23, -v12, v22, v21
	v_fmac_f32_e32 v22, v23, v14
	v_fma_f32 v12, -v12, v22, v21
	v_div_fmas_f32 v12, v12, v14, v22
	v_div_fixup_f32 v10, v12, v11, v10
	ds_write_b32 v34, v10 offset:57344
	s_waitcnt vmcnt(2)
	v_mov_b32_e32 v10, v29
	v_mul_f32_e32 v11, 0xbfb8aa3b, v10
	v_rndne_f32_e32 v14, v11
	v_fma_f32 v15, v10, s17, -v11
	v_sub_f32_e32 v11, v11, v14
	v_fmac_f32_e32 v15, 0xb2a5705f, v10
	v_add_f32_e32 v11, v11, v15
	v_cvt_i32_f32_e32 v14, v14
	v_exp_f32_e32 v11, v11
	v_cmp_nlt_f32_e64 s[46:47], s18, v10
	s_nop 0
	v_ldexp_f32 v11, v11, v14
	v_cndmask_b32_e64 v11, 0, v11, s[46:47]
	v_cmp_ngt_f32_e64 s[46:47], s19, v10
	s_nop 1
	v_cndmask_b32_e64 v11, v205, v11, s[46:47]
	v_add_f32_e32 v11, 1.0, v11
	v_div_scale_f32 v12, s[46:47], v11, v11, v10
	v_rcp_f32_e32 v14, v12
	v_div_scale_f32 v21, vcc, v10, v11, v10
	v_fma_f32 v22, -v12, v14, 1.0
	v_fmac_f32_e32 v14, v22, v14
	v_mul_f32_e32 v22, v21, v14
	v_fma_f32 v23, -v12, v22, v21
	v_fmac_f32_e32 v22, v23, v14
	v_fma_f32 v12, -v12, v22, v21
	v_div_fmas_f32 v12, v12, v14, v22
	v_div_fixup_f32 v10, v12, v11, v10
	ds_write_b32 v34, v10 offset:59392
	s_waitcnt vmcnt(1)
	v_mov_b32_e32 v10, v30
	v_mul_f32_e32 v11, 0xbfb8aa3b, v10
	v_rndne_f32_e32 v14, v11
	v_fma_f32 v15, v10, s17, -v11
	v_sub_f32_e32 v11, v11, v14
	v_fmac_f32_e32 v15, 0xb2a5705f, v10
	v_add_f32_e32 v11, v11, v15
	v_cvt_i32_f32_e32 v14, v14
	v_exp_f32_e32 v11, v11
	v_cmp_nlt_f32_e64 s[46:47], s18, v10
	s_nop 0
	v_ldexp_f32 v11, v11, v14
	v_cndmask_b32_e64 v11, 0, v11, s[46:47]
	v_cmp_ngt_f32_e64 s[46:47], s19, v10
	s_nop 1
	v_cndmask_b32_e64 v11, v205, v11, s[46:47]
	v_add_f32_e32 v11, 1.0, v11
	v_div_scale_f32 v12, s[46:47], v11, v11, v10
	v_rcp_f32_e32 v14, v12
	v_div_scale_f32 v21, vcc, v10, v11, v10
	v_fma_f32 v22, -v12, v14, 1.0
	v_fmac_f32_e32 v14, v22, v14
	v_mul_f32_e32 v22, v21, v14
	v_fma_f32 v23, -v12, v22, v21
	v_fmac_f32_e32 v22, v23, v14
	v_fma_f32 v12, -v12, v22, v21
	v_div_fmas_f32 v12, v12, v14, v22
	v_div_fixup_f32 v10, v12, v11, v10
	ds_write_b32 v34, v10 offset:61440
	s_waitcnt vmcnt(0)
	v_mov_b32_e32 v10, v31
	v_mul_f32_e32 v11, 0xbfb8aa3b, v10
	v_rndne_f32_e32 v14, v11
	v_fma_f32 v15, v10, s17, -v11
	v_sub_f32_e32 v11, v11, v14
	v_fmac_f32_e32 v15, 0xb2a5705f, v10
	v_add_f32_e32 v11, v11, v15
	v_cvt_i32_f32_e32 v14, v14
	v_exp_f32_e32 v11, v11
	v_cmp_nlt_f32_e64 s[46:47], s18, v10
	s_nop 0
	v_ldexp_f32 v11, v11, v14
	v_cndmask_b32_e64 v11, 0, v11, s[46:47]
	v_cmp_ngt_f32_e64 s[46:47], s19, v10
	s_nop 1
	v_cndmask_b32_e64 v11, v205, v11, s[46:47]
	v_add_f32_e32 v11, 1.0, v11
	v_div_scale_f32 v12, s[46:47], v11, v11, v10
	v_rcp_f32_e32 v14, v12
	v_div_scale_f32 v21, vcc, v10, v11, v10
	v_fma_f32 v22, -v12, v14, 1.0
	v_fmac_f32_e32 v14, v22, v14
	v_mul_f32_e32 v22, v21, v14
	v_fma_f32 v23, -v12, v22, v21
	v_fmac_f32_e32 v22, v23, v14
	v_fma_f32 v12, -v12, v22, v21
	v_div_fmas_f32 v12, v12, v14, v22
	v_div_fixup_f32 v10, v12, v11, v10
	ds_write_b32 v34, v10 offset:63488
	global_load_dword v24, v32, s[10:11]
	v_add_u32_e32 v33, 0x800, v32
	global_load_dword v25, v33, s[10:11]
	v_add_u32_e32 v33, 0x1000, v32
	global_load_dword v26, v33, s[10:11]
	v_add_u32_e32 v33, 0x1800, v32
	global_load_dword v27, v33, s[10:11]
	v_add_u32_e32 v33, 0x2000, v32
	global_load_dword v28, v33, s[10:11]
	v_add_u32_e32 v33, 0x2800, v32
	global_load_dword v29, v33, s[10:11]
	v_add_u32_e32 v33, 0x3000, v32
	global_load_dword v30, v33, s[10:11]
	v_add_u32_e32 v33, 0x3800, v32
	global_load_dword v31, v33, s[10:11]
	s_waitcnt vmcnt(7)
	v_mov_b32_e32 v10, v24
	v_mul_f32_e32 v11, 0xbfb8aa3b, v10
	v_rndne_f32_e32 v14, v11
	v_fma_f32 v15, v10, s17, -v11
	v_sub_f32_e32 v11, v11, v14
	v_fmac_f32_e32 v15, 0xb2a5705f, v10
	v_add_f32_e32 v11, v11, v15
	v_cvt_i32_f32_e32 v14, v14
	v_exp_f32_e32 v11, v11
	v_cmp_nlt_f32_e64 s[46:47], s18, v10
	s_nop 0
	v_ldexp_f32 v11, v11, v14
	v_cndmask_b32_e64 v11, 0, v11, s[46:47]
	v_cmp_ngt_f32_e64 s[46:47], s19, v10
	s_nop 1
	v_cndmask_b32_e64 v11, v205, v11, s[46:47]
	v_add_f32_e32 v11, 1.0, v11
	v_div_scale_f32 v12, s[46:47], v11, v11, v10
	v_rcp_f32_e32 v14, v12
	v_div_scale_f32 v21, vcc, v10, v11, v10
	v_fma_f32 v22, -v12, v14, 1.0
	v_fmac_f32_e32 v14, v22, v14
	v_mul_f32_e32 v22, v21, v14
	v_fma_f32 v23, -v12, v22, v21
	v_fmac_f32_e32 v22, v23, v14
	v_fma_f32 v12, -v12, v22, v21
	v_div_fmas_f32 v12, v12, v14, v22
	v_div_fixup_f32 v10, v12, v11, v10
	ds_write_b32 v35, v10
	s_waitcnt vmcnt(6)
	v_mov_b32_e32 v10, v25
	v_mul_f32_e32 v11, 0xbfb8aa3b, v10
	v_rndne_f32_e32 v14, v11
	v_fma_f32 v15, v10, s17, -v11
	v_sub_f32_e32 v11, v11, v14
	v_fmac_f32_e32 v15, 0xb2a5705f, v10
	v_add_f32_e32 v11, v11, v15
	v_cvt_i32_f32_e32 v14, v14
	v_exp_f32_e32 v11, v11
	v_cmp_nlt_f32_e64 s[46:47], s18, v10
	s_nop 0
	v_ldexp_f32 v11, v11, v14
	v_cndmask_b32_e64 v11, 0, v11, s[46:47]
	v_cmp_ngt_f32_e64 s[46:47], s19, v10
	s_nop 1
	v_cndmask_b32_e64 v11, v205, v11, s[46:47]
	v_add_f32_e32 v11, 1.0, v11
	v_div_scale_f32 v12, s[46:47], v11, v11, v10
	v_rcp_f32_e32 v14, v12
	v_div_scale_f32 v21, vcc, v10, v11, v10
	v_fma_f32 v22, -v12, v14, 1.0
	v_fmac_f32_e32 v14, v22, v14
	v_mul_f32_e32 v22, v21, v14
	v_fma_f32 v23, -v12, v22, v21
	v_fmac_f32_e32 v22, v23, v14
	v_fma_f32 v12, -v12, v22, v21
	v_div_fmas_f32 v12, v12, v14, v22
	v_div_fixup_f32 v10, v12, v11, v10
	ds_write_b32 v35, v10 offset:2048
	s_waitcnt vmcnt(5)
	v_mov_b32_e32 v10, v26
	v_mul_f32_e32 v11, 0xbfb8aa3b, v10
	v_rndne_f32_e32 v14, v11
	v_fma_f32 v15, v10, s17, -v11
	v_sub_f32_e32 v11, v11, v14
	v_fmac_f32_e32 v15, 0xb2a5705f, v10
	v_add_f32_e32 v11, v11, v15
	v_cvt_i32_f32_e32 v14, v14
	v_exp_f32_e32 v11, v11
	v_cmp_nlt_f32_e64 s[46:47], s18, v10
	s_nop 0
	v_ldexp_f32 v11, v11, v14
	v_cndmask_b32_e64 v11, 0, v11, s[46:47]
	v_cmp_ngt_f32_e64 s[46:47], s19, v10
	s_nop 1
	v_cndmask_b32_e64 v11, v205, v11, s[46:47]
	v_add_f32_e32 v11, 1.0, v11
	v_div_scale_f32 v12, s[46:47], v11, v11, v10
	v_rcp_f32_e32 v14, v12
	v_div_scale_f32 v21, vcc, v10, v11, v10
	v_fma_f32 v22, -v12, v14, 1.0
	v_fmac_f32_e32 v14, v22, v14
	v_mul_f32_e32 v22, v21, v14
	v_fma_f32 v23, -v12, v22, v21
	v_fmac_f32_e32 v22, v23, v14
	v_fma_f32 v12, -v12, v22, v21
	v_div_fmas_f32 v12, v12, v14, v22
	v_div_fixup_f32 v10, v12, v11, v10
	ds_write_b32 v35, v10 offset:4096
	s_waitcnt vmcnt(4)
	v_mov_b32_e32 v10, v27
	v_mul_f32_e32 v11, 0xbfb8aa3b, v10
	v_rndne_f32_e32 v14, v11
	v_fma_f32 v15, v10, s17, -v11
	v_sub_f32_e32 v11, v11, v14
	v_fmac_f32_e32 v15, 0xb2a5705f, v10
	v_add_f32_e32 v11, v11, v15
	v_cvt_i32_f32_e32 v14, v14
	v_exp_f32_e32 v11, v11
	v_cmp_nlt_f32_e64 s[46:47], s18, v10
	s_nop 0
	v_ldexp_f32 v11, v11, v14
	v_cndmask_b32_e64 v11, 0, v11, s[46:47]
	v_cmp_ngt_f32_e64 s[46:47], s19, v10
	s_nop 1
	v_cndmask_b32_e64 v11, v205, v11, s[46:47]
	v_add_f32_e32 v11, 1.0, v11
	v_div_scale_f32 v12, s[46:47], v11, v11, v10
	v_rcp_f32_e32 v14, v12
	v_div_scale_f32 v21, vcc, v10, v11, v10
	v_fma_f32 v22, -v12, v14, 1.0
	v_fmac_f32_e32 v14, v22, v14
	v_mul_f32_e32 v22, v21, v14
	v_fma_f32 v23, -v12, v22, v21
	v_fmac_f32_e32 v22, v23, v14
	v_fma_f32 v12, -v12, v22, v21
	v_div_fmas_f32 v12, v12, v14, v22
	v_div_fixup_f32 v10, v12, v11, v10
	ds_write_b32 v35, v10 offset:6144
	s_waitcnt vmcnt(3)
	v_mov_b32_e32 v10, v28
	v_mul_f32_e32 v11, 0xbfb8aa3b, v10
	v_rndne_f32_e32 v14, v11
	v_fma_f32 v15, v10, s17, -v11
	v_sub_f32_e32 v11, v11, v14
	v_fmac_f32_e32 v15, 0xb2a5705f, v10
	v_add_f32_e32 v11, v11, v15
	v_cvt_i32_f32_e32 v14, v14
	v_exp_f32_e32 v11, v11
	v_cmp_nlt_f32_e64 s[46:47], s18, v10
	s_nop 0
	v_ldexp_f32 v11, v11, v14
	v_cndmask_b32_e64 v11, 0, v11, s[46:47]
	v_cmp_ngt_f32_e64 s[46:47], s19, v10
	s_nop 1
	v_cndmask_b32_e64 v11, v205, v11, s[46:47]
	v_add_f32_e32 v11, 1.0, v11
	v_div_scale_f32 v12, s[46:47], v11, v11, v10
	v_rcp_f32_e32 v14, v12
	v_div_scale_f32 v21, vcc, v10, v11, v10
	v_fma_f32 v22, -v12, v14, 1.0
	v_fmac_f32_e32 v14, v22, v14
	v_mul_f32_e32 v22, v21, v14
	v_fma_f32 v23, -v12, v22, v21
	v_fmac_f32_e32 v22, v23, v14
	v_fma_f32 v12, -v12, v22, v21
	v_div_fmas_f32 v12, v12, v14, v22
	v_div_fixup_f32 v10, v12, v11, v10
	ds_write_b32 v35, v10 offset:8192
	s_waitcnt vmcnt(2)
	v_mov_b32_e32 v10, v29
	v_mul_f32_e32 v11, 0xbfb8aa3b, v10
	v_rndne_f32_e32 v14, v11
	v_fma_f32 v15, v10, s17, -v11
	v_sub_f32_e32 v11, v11, v14
	v_fmac_f32_e32 v15, 0xb2a5705f, v10
	v_add_f32_e32 v11, v11, v15
	v_cvt_i32_f32_e32 v14, v14
	v_exp_f32_e32 v11, v11
	v_cmp_nlt_f32_e64 s[46:47], s18, v10
	s_nop 0
	v_ldexp_f32 v11, v11, v14
	v_cndmask_b32_e64 v11, 0, v11, s[46:47]
	v_cmp_ngt_f32_e64 s[46:47], s19, v10
	s_nop 1
	v_cndmask_b32_e64 v11, v205, v11, s[46:47]
	v_add_f32_e32 v11, 1.0, v11
	v_div_scale_f32 v12, s[46:47], v11, v11, v10
	v_rcp_f32_e32 v14, v12
	v_div_scale_f32 v21, vcc, v10, v11, v10
	v_fma_f32 v22, -v12, v14, 1.0
	v_fmac_f32_e32 v14, v22, v14
	v_mul_f32_e32 v22, v21, v14
	v_fma_f32 v23, -v12, v22, v21
	v_fmac_f32_e32 v22, v23, v14
	v_fma_f32 v12, -v12, v22, v21
	v_div_fmas_f32 v12, v12, v14, v22
	v_div_fixup_f32 v10, v12, v11, v10
	ds_write_b32 v35, v10 offset:10240
	s_waitcnt vmcnt(1)
	v_mov_b32_e32 v10, v30
	v_mul_f32_e32 v11, 0xbfb8aa3b, v10
	v_rndne_f32_e32 v14, v11
	v_fma_f32 v15, v10, s17, -v11
	v_sub_f32_e32 v11, v11, v14
	v_fmac_f32_e32 v15, 0xb2a5705f, v10
	v_add_f32_e32 v11, v11, v15
	v_cvt_i32_f32_e32 v14, v14
	v_exp_f32_e32 v11, v11
	v_cmp_nlt_f32_e64 s[46:47], s18, v10
	s_nop 0
	v_ldexp_f32 v11, v11, v14
	v_cndmask_b32_e64 v11, 0, v11, s[46:47]
	v_cmp_ngt_f32_e64 s[46:47], s19, v10
	s_nop 1
	v_cndmask_b32_e64 v11, v205, v11, s[46:47]
	v_add_f32_e32 v11, 1.0, v11
	v_div_scale_f32 v12, s[46:47], v11, v11, v10
	v_rcp_f32_e32 v14, v12
	v_div_scale_f32 v21, vcc, v10, v11, v10
	v_fma_f32 v22, -v12, v14, 1.0
	v_fmac_f32_e32 v14, v22, v14
	v_mul_f32_e32 v22, v21, v14
	v_fma_f32 v23, -v12, v22, v21
	v_fmac_f32_e32 v22, v23, v14
	v_fma_f32 v12, -v12, v22, v21
	v_div_fmas_f32 v12, v12, v14, v22
	v_div_fixup_f32 v10, v12, v11, v10
	ds_write_b32 v35, v10 offset:12288
	s_waitcnt vmcnt(0)
	v_mov_b32_e32 v10, v31
	v_mul_f32_e32 v11, 0xbfb8aa3b, v10
	v_rndne_f32_e32 v14, v11
	v_fma_f32 v15, v10, s17, -v11
	v_sub_f32_e32 v11, v11, v14
	v_fmac_f32_e32 v15, 0xb2a5705f, v10
	v_add_f32_e32 v11, v11, v15
	v_cvt_i32_f32_e32 v14, v14
	v_exp_f32_e32 v11, v11
	v_cmp_nlt_f32_e64 s[46:47], s18, v10
	s_nop 0
	v_ldexp_f32 v11, v11, v14
	v_cndmask_b32_e64 v11, 0, v11, s[46:47]
	v_cmp_ngt_f32_e64 s[46:47], s19, v10
	s_nop 1
	v_cndmask_b32_e64 v11, v205, v11, s[46:47]
	v_add_f32_e32 v11, 1.0, v11
	v_div_scale_f32 v12, s[46:47], v11, v11, v10
	v_rcp_f32_e32 v14, v12
	v_div_scale_f32 v21, vcc, v10, v11, v10
	v_fma_f32 v22, -v12, v14, 1.0
	v_fmac_f32_e32 v14, v22, v14
	v_mul_f32_e32 v22, v21, v14
	v_fma_f32 v23, -v12, v22, v21
	v_fmac_f32_e32 v22, v23, v14
	v_fma_f32 v12, -v12, v22, v21
	v_div_fmas_f32 v12, v12, v14, v22
	v_div_fixup_f32 v10, v12, v11, v10
	ds_write_b32 v35, v10 offset:14336

.Lpb_next:
	s_add_i32 s65, s65, s3
	s_cmpk_lt_i32 s65, 0x440
	s_cbranch_scc1 .Lpb_loop
	s_branch .LBB0_178
	s_nop 0
	s_nop 0
	s_nop 0
	s_nop 0
	s_nop 0
	s_nop 0
	s_nop 0
	s_nop 0
	s_nop 0
	s_nop 0
	s_nop 0
	s_nop 0
	s_nop 0
	s_nop 0
	s_nop 0
	s_nop 0
	s_nop 0
	s_nop 0
	s_nop 0
	s_nop 0
	s_nop 0
	s_branch .LBB0_178
	s_nop 0
	s_nop 0
	s_nop 0
	s_nop 0
	s_nop 0
	s_nop 0
	s_nop 0
	s_nop 0
	s_nop 0
	s_nop 0
	s_nop 0
	s_nop 0
	s_nop 0
	s_nop 0
	s_nop 0
	s_nop 0
	s_nop 0
	s_nop 0
	s_nop 0
	s_nop 0
	s_nop 0
	s_nop 0
	s_nop 0
	s_nop 0
	s_nop 0
	s_nop 0
	s_nop 0
	s_nop 0
	s_nop 0
	s_nop 0
	s_nop 0
	s_nop 0
	s_nop 0
	s_nop 0
	s_nop 0
	s_nop 0
	s_nop 0
	s_nop 0
	s_nop 0
	s_nop 0
	s_nop 0
	s_nop 0
	s_nop 0
	s_nop 0
	s_nop 0
	s_nop 0
	s_nop 0
	s_nop 0
	s_nop 0

.LBB0_235:
	v_lshrrev_b32_e32 v18, 1, v16
	v_and_b32_e32 v18, 24, v18
	s_add_u32 s55, s6, 0x137b8000
	v_and_b32_e32 v17, 15, v16
	v_lshlrev_b32_e32 v19, 1, v18
	v_lshlrev_b32_e32 v16, 2, v16
	s_addc_u32 s56, s7, 0
	v_lshl_or_b32 v144, s9, 6, v17
	v_lshl_or_b32 v17, v17, 6, v19
	s_lshl_b32 s6, s9, 13
	v_and_b32_e32 v16, 32, v16
	v_bitop3_b32 v19, v17, s6, v16 bitop3:0xde
	s_lshl_b32 s6, s8, 5
	s_and_b32 s8, s6, 0x60
	s_add_i32 m0, s51, 0x18000
	v_lshl_add_u64 v[8:9], v[8:9], 0, s[36:37]
	s_lshl_b32 s6, s8, 7
	s_waitcnt vmcnt(2)
	s_barrier
	global_load_lds_dwordx4 v[8:9], off
	v_lshl_add_u64 v[6:7], v[6:7], 0, s[36:37]
	s_add_i32 m0, s51, 0x1a000
	s_add_i32 s57, s51, 0x8000
	s_add_i32 s58, s51, 0xa000
	v_bitop3_b32 v145, v17, s6, v16 bitop3:0xde
	global_load_lds_dwordx4 v[6:7], off
	v_lshl_add_u64 v[2:3], v[2:3], 0, s[36:37]
	s_mov_b32 m0, s57
	s_add_u32 s6, s44, 0x100080
	global_load_lds_dwordx4 v[2:3], off
	v_lshl_add_u64 v[2:3], v[4:5], 0, s[36:37]
	s_mov_b32 m0, s58
	s_addc_u32 s7, s45, 0
	global_load_lds_dwordx4 v[2:3], off
	s_add_i32 m0, s51, 0x1c000
	v_lshl_add_u64 v[2:3], s[6:7], 0, v[134:135]
	global_load_lds_dwordx4 v[2:3], off
	v_lshl_add_u64 v[2:3], s[6:7], 0, v[130:131]
	s_add_i32 m0, s51, 0x1e000
	s_cmpk_lt_u32 s0, 0x100
	global_load_lds_dwordx4 v[2:3], off
	v_lshlrev_b32_e32 v2, 16, v14
	v_and_b32_e32 v2, 0xfffe0000, v2
	v_lshl_add_u32 v2, v13, 13, v2
	v_and_b32_e32 v3, 1, v14
	v_lshl_or_b32 v2, v3, 6, v2
	v_lshl_add_u32 v138, v15, 1, v2
	v_lshlrev_b32_e32 v2, 16, v10
	v_and_b32_e32 v2, 0xfffe0000, v2
	s_waitcnt vmcnt(6)
	v_lshl_add_u32 v2, v11, 13, v2
	v_and_b32_e32 v3, 1, v10
	v_or_b32_e32 v146, s8, v18
	v_lshl_or_b32 v2, v3, 6, v2
	v_readlane_b32 s8, v254, 32
	s_cselect_b64 s[6:7], -1, 0
	v_mov_b32_e32 v139, v195
	v_lshl_add_u32 v140, v12, 1, v2
	v_mov_b32_e32 v141, v195
	s_mov_b32 s59, 0
	v_add_u32_e32 v147, 0, v19
	v_readlane_b32 s60, v254, 27
	s_mov_b32 s61, s8
	s_barrier
	v_readlane_b32 s9, v254, 33
	s_branch .LBB0_238
.Lmy_tr_acall:
	s_branch .Lmy_a_entry
.Lmy_tr_dret:
	s_branch .Lmy_d_ret
.LBB0_236:
	s_mov_b64 s[38:39], 0

.LBB0_695:
	v_lshl_add_u32 v148, s6, 8, v150
	s_lshl_b32 s0, s4, 8
	v_or_b32_e32 v149, s0, v152
	v_mov_b32_e32 v181, 0
	v_lshlrev_b32_e32 v180, 11, v148
	v_lshl_add_u32 v180, v149, 1, v180
	v_lshl_add_u64 v[142:143], s[40:41], 0, v[180:181]
	v_lshlrev_b32_e32 v180, 2, v149
	v_lshl_add_u64 v[178:179], s[46:47], 0, v[180:181]
	global_load_dwordx4 v[154:157], v[178:179], off
	global_load_dwordx4 v[158:161], v[178:179], off offset:16
	global_load_dwordx4 v[162:165], v[178:179], off offset:512
	global_load_dwordx4 v[166:169], v[178:179], off offset:528
	s_add_i32 s4, s0, 0x2400
	s_ashr_i32 s0, s4, 9
	s_mul_hi_i32 s4, s0, 0x1100000
	s_mul_i32 s0, s0, 0x1100000
	s_add_u32 s58, s65, s0
	s_addc_u32 s59, s66, s4
	v_and_b32_e32 v180, 0x1ff, v149
	v_lshlrev_b32_e32 v180, 1, v180
	v_lshl_add_u32 v180, v148, 10, v180
	v_lshl_add_u64 v[144:145], s[58:59], 0, v[180:181]
	v_lshlrev_b32_e32 v180, 13, v148
	v_lshl_add_u32 v180, v149, 1, v180
	v_add_u32_e32 v180, 0x1000, v180
	v_lshl_add_u64 v[146:147], s[44:45], 0, v[180:181]
	global_load_dwordx4 v[170:173], v[142:143], off
	global_load_dwordx4 v[174:177], v[144:145], off
	s_waitcnt vmcnt(2)
	v_pk_add_f32 v[126:127], v[126:127], v[154:155]
	v_pk_add_f32 v[122:123], v[122:123], v[158:159]
	v_pk_add_f32 v[128:129], v[128:129], v[156:157]
	v_pk_add_f32 v[124:125], v[124:125], v[160:161]
	v_pk_add_f32 v[118:119], v[118:119], v[162:163]
	v_pk_add_f32 v[114:115], v[114:115], v[166:167]
	v_pk_add_f32 v[120:121], v[120:121], v[164:165]
	v_pk_add_f32 v[116:117], v[116:117], v[168:169]
	v_pk_add_f32 v[110:111], v[110:111], v[154:155]
	v_pk_add_f32 v[106:107], v[106:107], v[158:159]
	v_pk_add_f32 v[112:113], v[112:113], v[156:157]
	v_pk_add_f32 v[108:109], v[108:109], v[160:161]
	v_pk_add_f32 v[102:103], v[102:103], v[162:163]
	v_pk_add_f32 v[98:99], v[98:99], v[166:167]
	v_pk_add_f32 v[104:105], v[104:105], v[164:165]
	v_pk_add_f32 v[100:101], v[100:101], v[168:169]
	v_pk_add_f32 v[94:95], v[94:95], v[154:155]
	v_pk_add_f32 v[90:91], v[90:91], v[158:159]
	v_pk_add_f32 v[96:97], v[96:97], v[156:157]
	v_pk_add_f32 v[92:93], v[92:93], v[160:161]
	v_pk_add_f32 v[86:87], v[86:87], v[162:163]
	v_pk_add_f32 v[82:83], v[82:83], v[166:167]
	v_pk_add_f32 v[88:89], v[88:89], v[164:165]
	v_pk_add_f32 v[84:85], v[84:85], v[168:169]
	v_pk_add_f32 v[78:79], v[78:79], v[154:155]
	v_pk_add_f32 v[74:75], v[74:75], v[158:159]
	v_pk_add_f32 v[80:81], v[80:81], v[156:157]
	v_pk_add_f32 v[76:77], v[76:77], v[160:161]
	v_pk_add_f32 v[70:71], v[70:71], v[162:163]
	v_pk_add_f32 v[66:67], v[66:67], v[166:167]
	v_pk_add_f32 v[72:73], v[72:73], v[164:165]
	v_pk_add_f32 v[68:69], v[68:69], v[168:169]
	v_pk_add_f32 v[62:63], v[62:63], v[154:155]
	v_pk_add_f32 v[58:59], v[58:59], v[158:159]
	v_pk_add_f32 v[64:65], v[64:65], v[156:157]
	v_pk_add_f32 v[60:61], v[60:61], v[160:161]
	v_pk_add_f32 v[54:55], v[54:55], v[162:163]
	v_pk_add_f32 v[50:51], v[50:51], v[166:167]
	v_pk_add_f32 v[56:57], v[56:57], v[164:165]
	v_pk_add_f32 v[52:53], v[52:53], v[168:169]
	v_pk_add_f32 v[46:47], v[46:47], v[154:155]
	v_pk_add_f32 v[42:43], v[42:43], v[158:159]
	v_pk_add_f32 v[48:49], v[48:49], v[156:157]
	v_pk_add_f32 v[44:45], v[44:45], v[160:161]
	v_pk_add_f32 v[38:39], v[38:39], v[162:163]
	v_pk_add_f32 v[34:35], v[34:35], v[166:167]
	v_pk_add_f32 v[40:41], v[40:41], v[164:165]
	v_pk_add_f32 v[36:37], v[36:37], v[168:169]
	v_pk_add_f32 v[30:31], v[30:31], v[154:155]
	v_pk_add_f32 v[26:27], v[26:27], v[158:159]
	v_pk_add_f32 v[32:33], v[32:33], v[156:157]
	v_pk_add_f32 v[28:29], v[28:29], v[160:161]
	v_pk_add_f32 v[22:23], v[22:23], v[162:163]
	v_pk_add_f32 v[18:19], v[18:19], v[166:167]
	v_pk_add_f32 v[24:25], v[24:25], v[164:165]
	v_pk_add_f32 v[20:21], v[20:21], v[168:169]
	v_pk_add_f32 v[14:15], v[14:15], v[154:155]
	v_pk_add_f32 v[10:11], v[10:11], v[158:159]
	v_pk_add_f32 v[16:17], v[16:17], v[156:157]
	v_pk_add_f32 v[12:13], v[12:13], v[160:161]
	v_pk_add_f32 v[6:7], v[6:7], v[162:163]
	v_pk_add_f32 v[2:3], v[2:3], v[166:167]
	v_pk_add_f32 v[8:9], v[8:9], v[164:165]
	v_pk_add_f32 v[4:5], v[4:5], v[168:169]
	global_load_dwordx4 v[154:157], v[142:143], off offset:256
	global_load_dwordx4 v[158:161], v[144:145], off offset:256
	s_mov_b64 s[58:59], 0x8000
	v_lshl_add_u64 v[142:143], v[142:143], 0, s[58:59]
	s_mov_b64 s[58:59], 0x4000
	v_lshl_add_u64 v[144:145], v[144:145], 0, s[58:59]
	global_load_dwordx4 v[162:165], v[142:143], off
	global_load_dwordx4 v[166:169], v[144:145], off
	s_waitcnt vmcnt(4)
	v_lshlrev_b32_e32 v178, 16, v170
	v_and_b32_e32 v170, 0xffff0000, v170
	v_lshlrev_b32_e32 v179, 16, v174
	v_and_b32_e32 v174, 0xffff0000, v174
	v_mul_f32_e32 v126, 0xbfb8aa3b, v126
	v_mul_f32_e32 v127, 0xbfb8aa3b, v127
	v_mul_f32_e32 v180, 0xbfb8aa3b, v179
	v_mul_f32_e32 v181, 0xbfb8aa3b, v174
	v_exp_f32_e32 v126, v126
	v_exp_f32_e32 v127, v127
	v_exp_f32_e32 v180, v180
	v_exp_f32_e32 v181, v181
	v_add_f32_e32 v126, 1.0, v126
	v_add_f32_e32 v127, 1.0, v127
	v_add_f32_e32 v180, 1.0, v180
	v_add_f32_e32 v181, 1.0, v181
	v_rcp_f32_e32 v126, v126
	v_rcp_f32_e32 v127, v127
	v_rcp_f32_e32 v180, v180
	v_rcp_f32_e32 v181, v181
	v_mul_f32_e32 v126, v126, v178
	v_mul_f32_e32 v127, v127, v170
	v_mul_f32_e32 v180, v180, v179
	v_mul_f32_e32 v181, v181, v174
	v_mul_f32_e32 v126, v126, v180
	v_mul_f32_e32 v127, v127, v181
	v_lshlrev_b32_e32 v178, 16, v171
	v_and_b32_e32 v171, 0xffff0000, v171
	v_lshlrev_b32_e32 v179, 16, v175
	v_and_b32_e32 v175, 0xffff0000, v175
	v_mul_f32_e32 v128, 0xbfb8aa3b, v128
	v_mul_f32_e32 v129, 0xbfb8aa3b, v129
	v_mul_f32_e32 v180, 0xbfb8aa3b, v179
	v_mul_f32_e32 v181, 0xbfb8aa3b, v175
	v_exp_f32_e32 v128, v128
	v_exp_f32_e32 v129, v129
	v_exp_f32_e32 v180, v180
	v_exp_f32_e32 v181, v181
	v_add_f32_e32 v128, 1.0, v128
	v_add_f32_e32 v129, 1.0, v129
	v_add_f32_e32 v180, 1.0, v180
	v_add_f32_e32 v181, 1.0, v181
	v_rcp_f32_e32 v128, v128
	v_rcp_f32_e32 v129, v129
	v_rcp_f32_e32 v180, v180
	v_rcp_f32_e32 v181, v181
	v_mul_f32_e32 v128, v128, v178
	v_mul_f32_e32 v129, v129, v171
	v_mul_f32_e32 v180, v180, v179
	v_mul_f32_e32 v181, v181, v175
	v_mul_f32_e32 v128, v128, v180
	v_mul_f32_e32 v129, v129, v181
	v_lshlrev_b32_e32 v178, 16, v172
	v_and_b32_e32 v172, 0xffff0000, v172
	v_lshlrev_b32_e32 v179, 16, v176
	v_and_b32_e32 v176, 0xffff0000, v176
	v_mul_f32_e32 v122, 0xbfb8aa3b, v122
	v_mul_f32_e32 v123, 0xbfb8aa3b, v123
	v_mul_f32_e32 v180, 0xbfb8aa3b, v179
	v_mul_f32_e32 v181, 0xbfb8aa3b, v176
	v_exp_f32_e32 v122, v122
	v_exp_f32_e32 v123, v123
	v_exp_f32_e32 v180, v180
	v_exp_f32_e32 v181, v181
	v_add_f32_e32 v122, 1.0, v122
	v_add_f32_e32 v123, 1.0, v123
	v_add_f32_e32 v180, 1.0, v180
	v_add_f32_e32 v181, 1.0, v181
	v_rcp_f32_e32 v122, v122
	v_rcp_f32_e32 v123, v123
	v_rcp_f32_e32 v180, v180
	v_rcp_f32_e32 v181, v181
	v_mul_f32_e32 v122, v122, v178
	v_mul_f32_e32 v123, v123, v172
	v_mul_f32_e32 v180, v180, v179
	v_mul_f32_e32 v181, v181, v176
	v_mul_f32_e32 v122, v122, v180
	v_mul_f32_e32 v123, v123, v181
	v_lshlrev_b32_e32 v178, 16, v173
	v_and_b32_e32 v173, 0xffff0000, v173
	v_lshlrev_b32_e32 v179, 16, v177
	v_and_b32_e32 v177, 0xffff0000, v177
	v_mul_f32_e32 v124, 0xbfb8aa3b, v124
	v_mul_f32_e32 v125, 0xbfb8aa3b, v125
	v_mul_f32_e32 v180, 0xbfb8aa3b, v179
	v_mul_f32_e32 v181, 0xbfb8aa3b, v177
	v_exp_f32_e32 v124, v124
	v_exp_f32_e32 v125, v125
	v_exp_f32_e32 v180, v180
	v_exp_f32_e32 v181, v181
	v_add_f32_e32 v124, 1.0, v124
	v_add_f32_e32 v125, 1.0, v125
	v_add_f32_e32 v180, 1.0, v180
	v_add_f32_e32 v181, 1.0, v181
	v_rcp_f32_e32 v124, v124
	v_rcp_f32_e32 v125, v125
	v_rcp_f32_e32 v180, v180
	v_rcp_f32_e32 v181, v181
	v_mul_f32_e32 v124, v124, v178
	v_mul_f32_e32 v125, v125, v173
	v_mul_f32_e32 v180, v180, v179
	v_mul_f32_e32 v181, v181, v177
	v_mul_f32_e32 v124, v124, v180
	v_mul_f32_e32 v125, v125, v181
	v_cvt_pk_bf16_f32 v126, v126, v127
	v_cvt_pk_bf16_f32 v127, v128, v129
	v_cvt_pk_bf16_f32 v128, v122, v123
	v_cvt_pk_bf16_f32 v129, v124, v125
	global_store_dwordx4 v[146:147], v[126:129], off
	global_load_dwordx4 v[170:173], v[142:143], off offset:256
	global_load_dwordx4 v[174:177], v[144:145], off offset:256
	s_waitcnt vmcnt(5)
	v_lshlrev_b32_e32 v178, 16, v154
	v_and_b32_e32 v154, 0xffff0000, v154
	v_lshlrev_b32_e32 v179, 16, v158
	v_and_b32_e32 v158, 0xffff0000, v158
	v_mul_f32_e32 v118, 0xbfb8aa3b, v118
	v_mul_f32_e32 v119, 0xbfb8aa3b, v119
	v_mul_f32_e32 v180, 0xbfb8aa3b, v179
	v_mul_f32_e32 v181, 0xbfb8aa3b, v158
	v_exp_f32_e32 v118, v118
	v_exp_f32_e32 v119, v119
	v_exp_f32_e32 v180, v180
	v_exp_f32_e32 v181, v181
	v_add_f32_e32 v118, 1.0, v118
	v_add_f32_e32 v119, 1.0, v119
	v_add_f32_e32 v180, 1.0, v180
	v_add_f32_e32 v181, 1.0, v181
	v_rcp_f32_e32 v118, v118
	v_rcp_f32_e32 v119, v119
	v_rcp_f32_e32 v180, v180
	v_rcp_f32_e32 v181, v181
	v_mul_f32_e32 v118, v118, v178
	v_mul_f32_e32 v119, v119, v154
	v_mul_f32_e32 v180, v180, v179
	v_mul_f32_e32 v181, v181, v158
	v_mul_f32_e32 v118, v118, v180
	v_mul_f32_e32 v119, v119, v181
	v_lshlrev_b32_e32 v178, 16, v155
	v_and_b32_e32 v155, 0xffff0000, v155
	v_lshlrev_b32_e32 v179, 16, v159
	v_and_b32_e32 v159, 0xffff0000, v159
	v_mul_f32_e32 v120, 0xbfb8aa3b, v120
	v_mul_f32_e32 v121, 0xbfb8aa3b, v121
	v_mul_f32_e32 v180, 0xbfb8aa3b, v179
	v_mul_f32_e32 v181, 0xbfb8aa3b, v159
	v_exp_f32_e32 v120, v120
	v_exp_f32_e32 v121, v121
	v_exp_f32_e32 v180, v180
	v_exp_f32_e32 v181, v181
	v_add_f32_e32 v120, 1.0, v120
	v_add_f32_e32 v121, 1.0, v121
	v_add_f32_e32 v180, 1.0, v180
	v_add_f32_e32 v181, 1.0, v181
	v_rcp_f32_e32 v120, v120
	v_rcp_f32_e32 v121, v121
	v_rcp_f32_e32 v180, v180
	v_rcp_f32_e32 v181, v181
	v_mul_f32_e32 v120, v120, v178
	v_mul_f32_e32 v121, v121, v155
	v_mul_f32_e32 v180, v180, v179
	v_mul_f32_e32 v181, v181, v159
	v_mul_f32_e32 v120, v120, v180
	v_mul_f32_e32 v121, v121, v181
	v_lshlrev_b32_e32 v178, 16, v156
	v_and_b32_e32 v156, 0xffff0000, v156
	v_lshlrev_b32_e32 v179, 16, v160
	v_and_b32_e32 v160, 0xffff0000, v160
	v_mul_f32_e32 v114, 0xbfb8aa3b, v114
	v_mul_f32_e32 v115, 0xbfb8aa3b, v115
	v_mul_f32_e32 v180, 0xbfb8aa3b, v179
	v_mul_f32_e32 v181, 0xbfb8aa3b, v160
	v_exp_f32_e32 v114, v114
	v_exp_f32_e32 v115, v115
	v_exp_f32_e32 v180, v180
	v_exp_f32_e32 v181, v181
	v_add_f32_e32 v114, 1.0, v114
	v_add_f32_e32 v115, 1.0, v115
	v_add_f32_e32 v180, 1.0, v180
	v_add_f32_e32 v181, 1.0, v181
	v_rcp_f32_e32 v114, v114
	v_rcp_f32_e32 v115, v115
	v_rcp_f32_e32 v180, v180
	v_rcp_f32_e32 v181, v181
	v_mul_f32_e32 v114, v114, v178
	v_mul_f32_e32 v115, v115, v156
	v_mul_f32_e32 v180, v180, v179
	v_mul_f32_e32 v181, v181, v160
	v_mul_f32_e32 v114, v114, v180
	v_mul_f32_e32 v115, v115, v181
	v_lshlrev_b32_e32 v178, 16, v157
	v_and_b32_e32 v157, 0xffff0000, v157
	v_lshlrev_b32_e32 v179, 16, v161
	v_and_b32_e32 v161, 0xffff0000, v161
	v_mul_f32_e32 v116, 0xbfb8aa3b, v116
	v_mul_f32_e32 v117, 0xbfb8aa3b, v117
	v_mul_f32_e32 v180, 0xbfb8aa3b, v179
	v_mul_f32_e32 v181, 0xbfb8aa3b, v161
	v_exp_f32_e32 v116, v116
	v_exp_f32_e32 v117, v117
	v_exp_f32_e32 v180, v180
	v_exp_f32_e32 v181, v181
	v_add_f32_e32 v116, 1.0, v116
	v_add_f32_e32 v117, 1.0, v117
	v_add_f32_e32 v180, 1.0, v180
	v_add_f32_e32 v181, 1.0, v181
	v_rcp_f32_e32 v116, v116
	v_rcp_f32_e32 v117, v117
	v_rcp_f32_e32 v180, v180
	v_rcp_f32_e32 v181, v181
	v_mul_f32_e32 v116, v116, v178
	v_mul_f32_e32 v117, v117, v157
	v_mul_f32_e32 v180, v180, v179
	v_mul_f32_e32 v181, v181, v161
	v_mul_f32_e32 v116, v116, v180
	v_mul_f32_e32 v117, v117, v181
	v_cvt_pk_bf16_f32 v118, v118, v119
	v_cvt_pk_bf16_f32 v119, v120, v121
	v_cvt_pk_bf16_f32 v120, v114, v115
	v_cvt_pk_bf16_f32 v121, v116, v117
	global_store_dwordx4 v[146:147], v[118:121], off offset:256
	s_mov_b64 s[58:59], 0x20000
	v_lshl_add_u64 v[146:147], v[146:147], 0, s[58:59]
	s_mov_b64 s[58:59], 0x8000
	v_lshl_add_u64 v[142:143], v[142:143], 0, s[58:59]
	s_mov_b64 s[58:59], 0x4000
	v_lshl_add_u64 v[144:145], v[144:145], 0, s[58:59]
	global_load_dwordx4 v[154:157], v[142:143], off
	global_load_dwordx4 v[158:161], v[144:145], off
	s_waitcnt vmcnt(6)
	v_lshlrev_b32_e32 v178, 16, v162
	v_and_b32_e32 v162, 0xffff0000, v162
	v_lshlrev_b32_e32 v179, 16, v166
	v_and_b32_e32 v166, 0xffff0000, v166
	v_mul_f32_e32 v110, 0xbfb8aa3b, v110
	v_mul_f32_e32 v111, 0xbfb8aa3b, v111
	v_mul_f32_e32 v180, 0xbfb8aa3b, v179
	v_mul_f32_e32 v181, 0xbfb8aa3b, v166
	v_exp_f32_e32 v110, v110
	v_exp_f32_e32 v111, v111
	v_exp_f32_e32 v180, v180
	v_exp_f32_e32 v181, v181
	v_add_f32_e32 v110, 1.0, v110
	v_add_f32_e32 v111, 1.0, v111
	v_add_f32_e32 v180, 1.0, v180
	v_add_f32_e32 v181, 1.0, v181
	v_rcp_f32_e32 v110, v110
	v_rcp_f32_e32 v111, v111
	v_rcp_f32_e32 v180, v180
	v_rcp_f32_e32 v181, v181
	v_mul_f32_e32 v110, v110, v178
	v_mul_f32_e32 v111, v111, v162
	v_mul_f32_e32 v180, v180, v179
	v_mul_f32_e32 v181, v181, v166
	v_mul_f32_e32 v110, v110, v180
	v_mul_f32_e32 v111, v111, v181
	v_lshlrev_b32_e32 v178, 16, v163
	v_and_b32_e32 v163, 0xffff0000, v163
	v_lshlrev_b32_e32 v179, 16, v167
	v_and_b32_e32 v167, 0xffff0000, v167
	v_mul_f32_e32 v112, 0xbfb8aa3b, v112
	v_mul_f32_e32 v113, 0xbfb8aa3b, v113
	v_mul_f32_e32 v180, 0xbfb8aa3b, v179
	v_mul_f32_e32 v181, 0xbfb8aa3b, v167
	v_exp_f32_e32 v112, v112
	v_exp_f32_e32 v113, v113
	v_exp_f32_e32 v180, v180
	v_exp_f32_e32 v181, v181
	v_add_f32_e32 v112, 1.0, v112
	v_add_f32_e32 v113, 1.0, v113
	v_add_f32_e32 v180, 1.0, v180
	v_add_f32_e32 v181, 1.0, v181
	v_rcp_f32_e32 v112, v112
	v_rcp_f32_e32 v113, v113
	v_rcp_f32_e32 v180, v180
	v_rcp_f32_e32 v181, v181
	v_mul_f32_e32 v112, v112, v178
	v_mul_f32_e32 v113, v113, v163
	v_mul_f32_e32 v180, v180, v179
	v_mul_f32_e32 v181, v181, v167
	v_mul_f32_e32 v112, v112, v180
	v_mul_f32_e32 v113, v113, v181
	v_lshlrev_b32_e32 v178, 16, v164
	v_and_b32_e32 v164, 0xffff0000, v164
	v_lshlrev_b32_e32 v179, 16, v168
	v_and_b32_e32 v168, 0xffff0000, v168
	v_mul_f32_e32 v106, 0xbfb8aa3b, v106
	v_mul_f32_e32 v107, 0xbfb8aa3b, v107
	v_mul_f32_e32 v180, 0xbfb8aa3b, v179
	v_mul_f32_e32 v181, 0xbfb8aa3b, v168
	v_exp_f32_e32 v106, v106
	v_exp_f32_e32 v107, v107
	v_exp_f32_e32 v180, v180
	v_exp_f32_e32 v181, v181
	v_add_f32_e32 v106, 1.0, v106
	v_add_f32_e32 v107, 1.0, v107
	v_add_f32_e32 v180, 1.0, v180
	v_add_f32_e32 v181, 1.0, v181
	v_rcp_f32_e32 v106, v106
	v_rcp_f32_e32 v107, v107
	v_rcp_f32_e32 v180, v180
	v_rcp_f32_e32 v181, v181
	v_mul_f32_e32 v106, v106, v178
	v_mul_f32_e32 v107, v107, v164
	v_mul_f32_e32 v180, v180, v179
	v_mul_f32_e32 v181, v181, v168
	v_mul_f32_e32 v106, v106, v180
	v_mul_f32_e32 v107, v107, v181
	v_lshlrev_b32_e32 v178, 16, v165
	v_and_b32_e32 v165, 0xffff0000, v165
	v_lshlrev_b32_e32 v179, 16, v169
	v_and_b32_e32 v169, 0xffff0000, v169
	v_mul_f32_e32 v108, 0xbfb8aa3b, v108
	v_mul_f32_e32 v109, 0xbfb8aa3b, v109
	v_mul_f32_e32 v180, 0xbfb8aa3b, v179
	v_mul_f32_e32 v181, 0xbfb8aa3b, v169
	v_exp_f32_e32 v108, v108
	v_exp_f32_e32 v109, v109
	v_exp_f32_e32 v180, v180
	v_exp_f32_e32 v181, v181
	v_add_f32_e32 v108, 1.0, v108
	v_add_f32_e32 v109, 1.0, v109
	v_add_f32_e32 v180, 1.0, v180
	v_add_f32_e32 v181, 1.0, v181
	v_rcp_f32_e32 v108, v108
	v_rcp_f32_e32 v109, v109
	v_rcp_f32_e32 v180, v180
	v_rcp_f32_e32 v181, v181
	v_mul_f32_e32 v108, v108, v178
	v_mul_f32_e32 v109, v109, v165
	v_mul_f32_e32 v180, v180, v179
	v_mul_f32_e32 v181, v181, v169
	v_mul_f32_e32 v108, v108, v180
	v_mul_f32_e32 v109, v109, v181
	v_cvt_pk_bf16_f32 v110, v110, v111
	v_cvt_pk_bf16_f32 v111, v112, v113
	v_cvt_pk_bf16_f32 v112, v106, v107
	v_cvt_pk_bf16_f32 v113, v108, v109
	global_store_dwordx4 v[146:147], v[110:113], off
	global_load_dwordx4 v[162:165], v[142:143], off offset:256
	global_load_dwordx4 v[166:169], v[144:145], off offset:256
	s_waitcnt vmcnt(6)
	v_lshlrev_b32_e32 v178, 16, v170
	v_and_b32_e32 v170, 0xffff0000, v170
	v_lshlrev_b32_e32 v179, 16, v174
	v_and_b32_e32 v174, 0xffff0000, v174
	v_mul_f32_e32 v102, 0xbfb8aa3b, v102
	v_mul_f32_e32 v103, 0xbfb8aa3b, v103
	v_mul_f32_e32 v180, 0xbfb8aa3b, v179
	v_mul_f32_e32 v181, 0xbfb8aa3b, v174
	v_exp_f32_e32 v102, v102
	v_exp_f32_e32 v103, v103
	v_exp_f32_e32 v180, v180
	v_exp_f32_e32 v181, v181
	v_add_f32_e32 v102, 1.0, v102
	v_add_f32_e32 v103, 1.0, v103
	v_add_f32_e32 v180, 1.0, v180
	v_add_f32_e32 v181, 1.0, v181
	v_rcp_f32_e32 v102, v102
	v_rcp_f32_e32 v103, v103
	v_rcp_f32_e32 v180, v180
	v_rcp_f32_e32 v181, v181
	v_mul_f32_e32 v102, v102, v178
	v_mul_f32_e32 v103, v103, v170
	v_mul_f32_e32 v180, v180, v179
	v_mul_f32_e32 v181, v181, v174
	v_mul_f32_e32 v102, v102, v180
	v_mul_f32_e32 v103, v103, v181
	v_lshlrev_b32_e32 v178, 16, v171
	v_and_b32_e32 v171, 0xffff0000, v171
	v_lshlrev_b32_e32 v179, 16, v175
	v_and_b32_e32 v175, 0xffff0000, v175
	v_mul_f32_e32 v104, 0xbfb8aa3b, v104
	v_mul_f32_e32 v105, 0xbfb8aa3b, v105
	v_mul_f32_e32 v180, 0xbfb8aa3b, v179
	v_mul_f32_e32 v181, 0xbfb8aa3b, v175
	v_exp_f32_e32 v104, v104
	v_exp_f32_e32 v105, v105
	v_exp_f32_e32 v180, v180
	v_exp_f32_e32 v181, v181
	v_add_f32_e32 v104, 1.0, v104
	v_add_f32_e32 v105, 1.0, v105
	v_add_f32_e32 v180, 1.0, v180
	v_add_f32_e32 v181, 1.0, v181
	v_rcp_f32_e32 v104, v104
	v_rcp_f32_e32 v105, v105
	v_rcp_f32_e32 v180, v180
	v_rcp_f32_e32 v181, v181
	v_mul_f32_e32 v104, v104, v178
	v_mul_f32_e32 v105, v105, v171
	v_mul_f32_e32 v180, v180, v179
	v_mul_f32_e32 v181, v181, v175
	v_mul_f32_e32 v104, v104, v180
	v_mul_f32_e32 v105, v105, v181
	v_lshlrev_b32_e32 v178, 16, v172
	v_and_b32_e32 v172, 0xffff0000, v172
	v_lshlrev_b32_e32 v179, 16, v176
	v_and_b32_e32 v176, 0xffff0000, v176
	v_mul_f32_e32 v98, 0xbfb8aa3b, v98
	v_mul_f32_e32 v99, 0xbfb8aa3b, v99
	v_mul_f32_e32 v180, 0xbfb8aa3b, v179
	v_mul_f32_e32 v181, 0xbfb8aa3b, v176
	v_exp_f32_e32 v98, v98
	v_exp_f32_e32 v99, v99
	v_exp_f32_e32 v180, v180
	v_exp_f32_e32 v181, v181
	v_add_f32_e32 v98, 1.0, v98
	v_add_f32_e32 v99, 1.0, v99
	v_add_f32_e32 v180, 1.0, v180
	v_add_f32_e32 v181, 1.0, v181
	v_rcp_f32_e32 v98, v98
	v_rcp_f32_e32 v99, v99
	v_rcp_f32_e32 v180, v180
	v_rcp_f32_e32 v181, v181
	v_mul_f32_e32 v98, v98, v178
	v_mul_f32_e32 v99, v99, v172
	v_mul_f32_e32 v180, v180, v179
	v_mul_f32_e32 v181, v181, v176
	v_mul_f32_e32 v98, v98, v180
	v_mul_f32_e32 v99, v99, v181
	v_lshlrev_b32_e32 v178, 16, v173
	v_and_b32_e32 v173, 0xffff0000, v173
	v_lshlrev_b32_e32 v179, 16, v177
	v_and_b32_e32 v177, 0xffff0000, v177
	v_mul_f32_e32 v100, 0xbfb8aa3b, v100
	v_mul_f32_e32 v101, 0xbfb8aa3b, v101
	v_mul_f32_e32 v180, 0xbfb8aa3b, v179
	v_mul_f32_e32 v181, 0xbfb8aa3b, v177
	v_exp_f32_e32 v100, v100
	v_exp_f32_e32 v101, v101
	v_exp_f32_e32 v180, v180
	v_exp_f32_e32 v181, v181
	v_add_f32_e32 v100, 1.0, v100
	v_add_f32_e32 v101, 1.0, v101
	v_add_f32_e32 v180, 1.0, v180
	v_add_f32_e32 v181, 1.0, v181
	v_rcp_f32_e32 v100, v100
	v_rcp_f32_e32 v101, v101
	v_rcp_f32_e32 v180, v180
	v_rcp_f32_e32 v181, v181
	v_mul_f32_e32 v100, v100, v178
	v_mul_f32_e32 v101, v101, v173
	v_mul_f32_e32 v180, v180, v179
	v_mul_f32_e32 v181, v181, v177
	v_mul_f32_e32 v100, v100, v180
	v_mul_f32_e32 v101, v101, v181
	v_cvt_pk_bf16_f32 v102, v102, v103
	v_cvt_pk_bf16_f32 v103, v104, v105
	v_cvt_pk_bf16_f32 v104, v98, v99
	v_cvt_pk_bf16_f32 v105, v100, v101
	global_store_dwordx4 v[146:147], v[102:105], off offset:256
	s_mov_b64 s[58:59], 0x20000
	v_lshl_add_u64 v[146:147], v[146:147], 0, s[58:59]
	s_mov_b64 s[58:59], 0x8000
	v_lshl_add_u64 v[142:143], v[142:143], 0, s[58:59]
	s_mov_b64 s[58:59], 0x4000
	v_lshl_add_u64 v[144:145], v[144:145], 0, s[58:59]
	global_load_dwordx4 v[170:173], v[142:143], off
	global_load_dwordx4 v[174:177], v[144:145], off
	s_waitcnt vmcnt(6)
	v_lshlrev_b32_e32 v178, 16, v154
	v_and_b32_e32 v154, 0xffff0000, v154
	v_lshlrev_b32_e32 v179, 16, v158
	v_and_b32_e32 v158, 0xffff0000, v158
	v_mul_f32_e32 v94, 0xbfb8aa3b, v94
	v_mul_f32_e32 v95, 0xbfb8aa3b, v95
	v_mul_f32_e32 v180, 0xbfb8aa3b, v179
	v_mul_f32_e32 v181, 0xbfb8aa3b, v158
	v_exp_f32_e32 v94, v94
	v_exp_f32_e32 v95, v95
	v_exp_f32_e32 v180, v180
	v_exp_f32_e32 v181, v181
	v_add_f32_e32 v94, 1.0, v94
	v_add_f32_e32 v95, 1.0, v95
	v_add_f32_e32 v180, 1.0, v180
	v_add_f32_e32 v181, 1.0, v181
	v_rcp_f32_e32 v94, v94
	v_rcp_f32_e32 v95, v95
	v_rcp_f32_e32 v180, v180
	v_rcp_f32_e32 v181, v181
	v_mul_f32_e32 v94, v94, v178
	v_mul_f32_e32 v95, v95, v154
	v_mul_f32_e32 v180, v180, v179
	v_mul_f32_e32 v181, v181, v158
	v_mul_f32_e32 v94, v94, v180
	v_mul_f32_e32 v95, v95, v181
	v_lshlrev_b32_e32 v178, 16, v155
	v_and_b32_e32 v155, 0xffff0000, v155
	v_lshlrev_b32_e32 v179, 16, v159
	v_and_b32_e32 v159, 0xffff0000, v159
	v_mul_f32_e32 v96, 0xbfb8aa3b, v96
	v_mul_f32_e32 v97, 0xbfb8aa3b, v97
	v_mul_f32_e32 v180, 0xbfb8aa3b, v179
	v_mul_f32_e32 v181, 0xbfb8aa3b, v159
	v_exp_f32_e32 v96, v96
	v_exp_f32_e32 v97, v97
	v_exp_f32_e32 v180, v180
	v_exp_f32_e32 v181, v181
	v_add_f32_e32 v96, 1.0, v96
	v_add_f32_e32 v97, 1.0, v97
	v_add_f32_e32 v180, 1.0, v180
	v_add_f32_e32 v181, 1.0, v181
	v_rcp_f32_e32 v96, v96
	v_rcp_f32_e32 v97, v97
	v_rcp_f32_e32 v180, v180
	v_rcp_f32_e32 v181, v181
	v_mul_f32_e32 v96, v96, v178
	v_mul_f32_e32 v97, v97, v155
	v_mul_f32_e32 v180, v180, v179
	v_mul_f32_e32 v181, v181, v159
	v_mul_f32_e32 v96, v96, v180
	v_mul_f32_e32 v97, v97, v181
	v_lshlrev_b32_e32 v178, 16, v156
	v_and_b32_e32 v156, 0xffff0000, v156
	v_lshlrev_b32_e32 v179, 16, v160
	v_and_b32_e32 v160, 0xffff0000, v160
	v_mul_f32_e32 v90, 0xbfb8aa3b, v90
	v_mul_f32_e32 v91, 0xbfb8aa3b, v91
	v_mul_f32_e32 v180, 0xbfb8aa3b, v179
	v_mul_f32_e32 v181, 0xbfb8aa3b, v160
	v_exp_f32_e32 v90, v90
	v_exp_f32_e32 v91, v91
	v_exp_f32_e32 v180, v180
	v_exp_f32_e32 v181, v181
	v_add_f32_e32 v90, 1.0, v90
	v_add_f32_e32 v91, 1.0, v91
	v_add_f32_e32 v180, 1.0, v180
	v_add_f32_e32 v181, 1.0, v181
	v_rcp_f32_e32 v90, v90
	v_rcp_f32_e32 v91, v91
	v_rcp_f32_e32 v180, v180
	v_rcp_f32_e32 v181, v181
	v_mul_f32_e32 v90, v90, v178
	v_mul_f32_e32 v91, v91, v156
	v_mul_f32_e32 v180, v180, v179
	v_mul_f32_e32 v181, v181, v160
	v_mul_f32_e32 v90, v90, v180
	v_mul_f32_e32 v91, v91, v181
	v_lshlrev_b32_e32 v178, 16, v157
	v_and_b32_e32 v157, 0xffff0000, v157
	v_lshlrev_b32_e32 v179, 16, v161
	v_and_b32_e32 v161, 0xffff0000, v161
	v_mul_f32_e32 v92, 0xbfb8aa3b, v92
	v_mul_f32_e32 v93, 0xbfb8aa3b, v93
	v_mul_f32_e32 v180, 0xbfb8aa3b, v179
	v_mul_f32_e32 v181, 0xbfb8aa3b, v161
	v_exp_f32_e32 v92, v92
	v_exp_f32_e32 v93, v93
	v_exp_f32_e32 v180, v180
	v_exp_f32_e32 v181, v181
	v_add_f32_e32 v92, 1.0, v92
	v_add_f32_e32 v93, 1.0, v93
	v_add_f32_e32 v180, 1.0, v180
	v_add_f32_e32 v181, 1.0, v181
	v_rcp_f32_e32 v92, v92
	v_rcp_f32_e32 v93, v93
	v_rcp_f32_e32 v180, v180
	v_rcp_f32_e32 v181, v181
	v_mul_f32_e32 v92, v92, v178
	v_mul_f32_e32 v93, v93, v157
	v_mul_f32_e32 v180, v180, v179
	v_mul_f32_e32 v181, v181, v161
	v_mul_f32_e32 v92, v92, v180
	v_mul_f32_e32 v93, v93, v181
	v_cvt_pk_bf16_f32 v94, v94, v95
	v_cvt_pk_bf16_f32 v95, v96, v97
	v_cvt_pk_bf16_f32 v96, v90, v91
	v_cvt_pk_bf16_f32 v97, v92, v93
	global_store_dwordx4 v[146:147], v[94:97], off
	global_load_dwordx4 v[154:157], v[142:143], off offset:256
	global_load_dwordx4 v[158:161], v[144:145], off offset:256
	s_waitcnt vmcnt(6)
	v_lshlrev_b32_e32 v178, 16, v162
	v_and_b32_e32 v162, 0xffff0000, v162
	v_lshlrev_b32_e32 v179, 16, v166
	v_and_b32_e32 v166, 0xffff0000, v166
	v_mul_f32_e32 v86, 0xbfb8aa3b, v86
	v_mul_f32_e32 v87, 0xbfb8aa3b, v87
	v_mul_f32_e32 v180, 0xbfb8aa3b, v179
	v_mul_f32_e32 v181, 0xbfb8aa3b, v166
	v_exp_f32_e32 v86, v86
	v_exp_f32_e32 v87, v87
	v_exp_f32_e32 v180, v180
	v_exp_f32_e32 v181, v181
	v_add_f32_e32 v86, 1.0, v86
	v_add_f32_e32 v87, 1.0, v87
	v_add_f32_e32 v180, 1.0, v180
	v_add_f32_e32 v181, 1.0, v181
	v_rcp_f32_e32 v86, v86
	v_rcp_f32_e32 v87, v87
	v_rcp_f32_e32 v180, v180
	v_rcp_f32_e32 v181, v181
	v_mul_f32_e32 v86, v86, v178
	v_mul_f32_e32 v87, v87, v162
	v_mul_f32_e32 v180, v180, v179
	v_mul_f32_e32 v181, v181, v166
	v_mul_f32_e32 v86, v86, v180
	v_mul_f32_e32 v87, v87, v181
	v_lshlrev_b32_e32 v178, 16, v163
	v_and_b32_e32 v163, 0xffff0000, v163
	v_lshlrev_b32_e32 v179, 16, v167
	v_and_b32_e32 v167, 0xffff0000, v167
	v_mul_f32_e32 v88, 0xbfb8aa3b, v88
	v_mul_f32_e32 v89, 0xbfb8aa3b, v89
	v_mul_f32_e32 v180, 0xbfb8aa3b, v179
	v_mul_f32_e32 v181, 0xbfb8aa3b, v167
	v_exp_f32_e32 v88, v88
	v_exp_f32_e32 v89, v89
	v_exp_f32_e32 v180, v180
	v_exp_f32_e32 v181, v181
	v_add_f32_e32 v88, 1.0, v88
	v_add_f32_e32 v89, 1.0, v89
	v_add_f32_e32 v180, 1.0, v180
	v_add_f32_e32 v181, 1.0, v181
	v_rcp_f32_e32 v88, v88
	v_rcp_f32_e32 v89, v89
	v_rcp_f32_e32 v180, v180
	v_rcp_f32_e32 v181, v181
	v_mul_f32_e32 v88, v88, v178
	v_mul_f32_e32 v89, v89, v163
	v_mul_f32_e32 v180, v180, v179
	v_mul_f32_e32 v181, v181, v167
	v_mul_f32_e32 v88, v88, v180
	v_mul_f32_e32 v89, v89, v181
	v_lshlrev_b32_e32 v178, 16, v164
	v_and_b32_e32 v164, 0xffff0000, v164
	v_lshlrev_b32_e32 v179, 16, v168
	v_and_b32_e32 v168, 0xffff0000, v168
	v_mul_f32_e32 v82, 0xbfb8aa3b, v82
	v_mul_f32_e32 v83, 0xbfb8aa3b, v83
	v_mul_f32_e32 v180, 0xbfb8aa3b, v179
	v_mul_f32_e32 v181, 0xbfb8aa3b, v168
	v_exp_f32_e32 v82, v82
	v_exp_f32_e32 v83, v83
	v_exp_f32_e32 v180, v180
	v_exp_f32_e32 v181, v181
	v_add_f32_e32 v82, 1.0, v82
	v_add_f32_e32 v83, 1.0, v83
	v_add_f32_e32 v180, 1.0, v180
	v_add_f32_e32 v181, 1.0, v181
	v_rcp_f32_e32 v82, v82
	v_rcp_f32_e32 v83, v83
	v_rcp_f32_e32 v180, v180
	v_rcp_f32_e32 v181, v181
	v_mul_f32_e32 v82, v82, v178
	v_mul_f32_e32 v83, v83, v164
	v_mul_f32_e32 v180, v180, v179
	v_mul_f32_e32 v181, v181, v168
	v_mul_f32_e32 v82, v82, v180
	v_mul_f32_e32 v83, v83, v181
	v_lshlrev_b32_e32 v178, 16, v165
	v_and_b32_e32 v165, 0xffff0000, v165
	v_lshlrev_b32_e32 v179, 16, v169
	v_and_b32_e32 v169, 0xffff0000, v169
	v_mul_f32_e32 v84, 0xbfb8aa3b, v84
	v_mul_f32_e32 v85, 0xbfb8aa3b, v85
	v_mul_f32_e32 v180, 0xbfb8aa3b, v179
	v_mul_f32_e32 v181, 0xbfb8aa3b, v169
	v_exp_f32_e32 v84, v84
	v_exp_f32_e32 v85, v85
	v_exp_f32_e32 v180, v180
	v_exp_f32_e32 v181, v181
	v_add_f32_e32 v84, 1.0, v84
	v_add_f32_e32 v85, 1.0, v85
	v_add_f32_e32 v180, 1.0, v180
	v_add_f32_e32 v181, 1.0, v181
	v_rcp_f32_e32 v84, v84
	v_rcp_f32_e32 v85, v85
	v_rcp_f32_e32 v180, v180
	v_rcp_f32_e32 v181, v181
	v_mul_f32_e32 v84, v84, v178
	v_mul_f32_e32 v85, v85, v165
	v_mul_f32_e32 v180, v180, v179
	v_mul_f32_e32 v181, v181, v169
	v_mul_f32_e32 v84, v84, v180
	v_mul_f32_e32 v85, v85, v181
	v_cvt_pk_bf16_f32 v86, v86, v87
	v_cvt_pk_bf16_f32 v87, v88, v89
	v_cvt_pk_bf16_f32 v88, v82, v83
	v_cvt_pk_bf16_f32 v89, v84, v85
	global_store_dwordx4 v[146:147], v[86:89], off offset:256
	s_mov_b64 s[58:59], 0x20000
	v_lshl_add_u64 v[146:147], v[146:147], 0, s[58:59]
	s_mov_b64 s[58:59], 0x28000
	v_lshl_add_u64 v[142:143], v[142:143], 0, s[58:59]
	s_mov_b64 s[58:59], 0x14000
	v_lshl_add_u64 v[144:145], v[144:145], 0, s[58:59]
	global_load_dwordx4 v[162:165], v[142:143], off
	global_load_dwordx4 v[166:169], v[144:145], off
	s_waitcnt vmcnt(6)
	v_lshlrev_b32_e32 v178, 16, v170
	v_and_b32_e32 v170, 0xffff0000, v170
	v_lshlrev_b32_e32 v179, 16, v174
	v_and_b32_e32 v174, 0xffff0000, v174
	v_mul_f32_e32 v78, 0xbfb8aa3b, v78
	v_mul_f32_e32 v79, 0xbfb8aa3b, v79
	v_mul_f32_e32 v180, 0xbfb8aa3b, v179
	v_mul_f32_e32 v181, 0xbfb8aa3b, v174
	v_exp_f32_e32 v78, v78
	v_exp_f32_e32 v79, v79
	v_exp_f32_e32 v180, v180
	v_exp_f32_e32 v181, v181
	v_add_f32_e32 v78, 1.0, v78
	v_add_f32_e32 v79, 1.0, v79
	v_add_f32_e32 v180, 1.0, v180
	v_add_f32_e32 v181, 1.0, v181
	v_rcp_f32_e32 v78, v78
	v_rcp_f32_e32 v79, v79
	v_rcp_f32_e32 v180, v180
	v_rcp_f32_e32 v181, v181
	v_mul_f32_e32 v78, v78, v178
	v_mul_f32_e32 v79, v79, v170
	v_mul_f32_e32 v180, v180, v179
	v_mul_f32_e32 v181, v181, v174
	v_mul_f32_e32 v78, v78, v180
	v_mul_f32_e32 v79, v79, v181
	v_lshlrev_b32_e32 v178, 16, v171
	v_and_b32_e32 v171, 0xffff0000, v171
	v_lshlrev_b32_e32 v179, 16, v175
	v_and_b32_e32 v175, 0xffff0000, v175
	v_mul_f32_e32 v80, 0xbfb8aa3b, v80
	v_mul_f32_e32 v81, 0xbfb8aa3b, v81
	v_mul_f32_e32 v180, 0xbfb8aa3b, v179
	v_mul_f32_e32 v181, 0xbfb8aa3b, v175
	v_exp_f32_e32 v80, v80
	v_exp_f32_e32 v81, v81
	v_exp_f32_e32 v180, v180
	v_exp_f32_e32 v181, v181
	v_add_f32_e32 v80, 1.0, v80
	v_add_f32_e32 v81, 1.0, v81
	v_add_f32_e32 v180, 1.0, v180
	v_add_f32_e32 v181, 1.0, v181
	v_rcp_f32_e32 v80, v80
	v_rcp_f32_e32 v81, v81
	v_rcp_f32_e32 v180, v180
	v_rcp_f32_e32 v181, v181
	v_mul_f32_e32 v80, v80, v178
	v_mul_f32_e32 v81, v81, v171
	v_mul_f32_e32 v180, v180, v179
	v_mul_f32_e32 v181, v181, v175
	v_mul_f32_e32 v80, v80, v180
	v_mul_f32_e32 v81, v81, v181
	v_lshlrev_b32_e32 v178, 16, v172
	v_and_b32_e32 v172, 0xffff0000, v172
	v_lshlrev_b32_e32 v179, 16, v176
	v_and_b32_e32 v176, 0xffff0000, v176
	v_mul_f32_e32 v74, 0xbfb8aa3b, v74
	v_mul_f32_e32 v75, 0xbfb8aa3b, v75
	v_mul_f32_e32 v180, 0xbfb8aa3b, v179
	v_mul_f32_e32 v181, 0xbfb8aa3b, v176
	v_exp_f32_e32 v74, v74
	v_exp_f32_e32 v75, v75
	v_exp_f32_e32 v180, v180
	v_exp_f32_e32 v181, v181
	v_add_f32_e32 v74, 1.0, v74
	v_add_f32_e32 v75, 1.0, v75
	v_add_f32_e32 v180, 1.0, v180
	v_add_f32_e32 v181, 1.0, v181
	v_rcp_f32_e32 v74, v74
	v_rcp_f32_e32 v75, v75
	v_rcp_f32_e32 v180, v180
	v_rcp_f32_e32 v181, v181
	v_mul_f32_e32 v74, v74, v178
	v_mul_f32_e32 v75, v75, v172
	v_mul_f32_e32 v180, v180, v179
	v_mul_f32_e32 v181, v181, v176
	v_mul_f32_e32 v74, v74, v180
	v_mul_f32_e32 v75, v75, v181
	v_lshlrev_b32_e32 v178, 16, v173
	v_and_b32_e32 v173, 0xffff0000, v173
	v_lshlrev_b32_e32 v179, 16, v177
	v_and_b32_e32 v177, 0xffff0000, v177
	v_mul_f32_e32 v76, 0xbfb8aa3b, v76
	v_mul_f32_e32 v77, 0xbfb8aa3b, v77
	v_mul_f32_e32 v180, 0xbfb8aa3b, v179
	v_mul_f32_e32 v181, 0xbfb8aa3b, v177
	v_exp_f32_e32 v76, v76
	v_exp_f32_e32 v77, v77
	v_exp_f32_e32 v180, v180
	v_exp_f32_e32 v181, v181
	v_add_f32_e32 v76, 1.0, v76
	v_add_f32_e32 v77, 1.0, v77
	v_add_f32_e32 v180, 1.0, v180
	v_add_f32_e32 v181, 1.0, v181
	v_rcp_f32_e32 v76, v76
	v_rcp_f32_e32 v77, v77
	v_rcp_f32_e32 v180, v180
	v_rcp_f32_e32 v181, v181
	v_mul_f32_e32 v76, v76, v178
	v_mul_f32_e32 v77, v77, v173
	v_mul_f32_e32 v180, v180, v179
	v_mul_f32_e32 v181, v181, v177
	v_mul_f32_e32 v76, v76, v180
	v_mul_f32_e32 v77, v77, v181
	v_cvt_pk_bf16_f32 v78, v78, v79
	v_cvt_pk_bf16_f32 v79, v80, v81
	v_cvt_pk_bf16_f32 v80, v74, v75
	v_cvt_pk_bf16_f32 v81, v76, v77
	global_store_dwordx4 v[146:147], v[78:81], off
	global_load_dwordx4 v[170:173], v[142:143], off offset:256
	global_load_dwordx4 v[174:177], v[144:145], off offset:256
	s_waitcnt vmcnt(6)
	v_lshlrev_b32_e32 v178, 16, v154
	v_and_b32_e32 v154, 0xffff0000, v154
	v_lshlrev_b32_e32 v179, 16, v158
	v_and_b32_e32 v158, 0xffff0000, v158
	v_mul_f32_e32 v70, 0xbfb8aa3b, v70
	v_mul_f32_e32 v71, 0xbfb8aa3b, v71
	v_mul_f32_e32 v180, 0xbfb8aa3b, v179
	v_mul_f32_e32 v181, 0xbfb8aa3b, v158
	v_exp_f32_e32 v70, v70
	v_exp_f32_e32 v71, v71
	v_exp_f32_e32 v180, v180
	v_exp_f32_e32 v181, v181
	v_add_f32_e32 v70, 1.0, v70
	v_add_f32_e32 v71, 1.0, v71
	v_add_f32_e32 v180, 1.0, v180
	v_add_f32_e32 v181, 1.0, v181
	v_rcp_f32_e32 v70, v70
	v_rcp_f32_e32 v71, v71
	v_rcp_f32_e32 v180, v180
	v_rcp_f32_e32 v181, v181
	v_mul_f32_e32 v70, v70, v178
	v_mul_f32_e32 v71, v71, v154
	v_mul_f32_e32 v180, v180, v179
	v_mul_f32_e32 v181, v181, v158
	v_mul_f32_e32 v70, v70, v180
	v_mul_f32_e32 v71, v71, v181
	v_lshlrev_b32_e32 v178, 16, v155
	v_and_b32_e32 v155, 0xffff0000, v155
	v_lshlrev_b32_e32 v179, 16, v159
	v_and_b32_e32 v159, 0xffff0000, v159
	v_mul_f32_e32 v72, 0xbfb8aa3b, v72
	v_mul_f32_e32 v73, 0xbfb8aa3b, v73
	v_mul_f32_e32 v180, 0xbfb8aa3b, v179
	v_mul_f32_e32 v181, 0xbfb8aa3b, v159
	v_exp_f32_e32 v72, v72
	v_exp_f32_e32 v73, v73
	v_exp_f32_e32 v180, v180
	v_exp_f32_e32 v181, v181
	v_add_f32_e32 v72, 1.0, v72
	v_add_f32_e32 v73, 1.0, v73
	v_add_f32_e32 v180, 1.0, v180
	v_add_f32_e32 v181, 1.0, v181
	v_rcp_f32_e32 v72, v72
	v_rcp_f32_e32 v73, v73
	v_rcp_f32_e32 v180, v180
	v_rcp_f32_e32 v181, v181
	v_mul_f32_e32 v72, v72, v178
	v_mul_f32_e32 v73, v73, v155
	v_mul_f32_e32 v180, v180, v179
	v_mul_f32_e32 v181, v181, v159
	v_mul_f32_e32 v72, v72, v180
	v_mul_f32_e32 v73, v73, v181
	v_lshlrev_b32_e32 v178, 16, v156
	v_and_b32_e32 v156, 0xffff0000, v156
	v_lshlrev_b32_e32 v179, 16, v160
	v_and_b32_e32 v160, 0xffff0000, v160
	v_mul_f32_e32 v66, 0xbfb8aa3b, v66
	v_mul_f32_e32 v67, 0xbfb8aa3b, v67
	v_mul_f32_e32 v180, 0xbfb8aa3b, v179
	v_mul_f32_e32 v181, 0xbfb8aa3b, v160
	v_exp_f32_e32 v66, v66
	v_exp_f32_e32 v67, v67
	v_exp_f32_e32 v180, v180
	v_exp_f32_e32 v181, v181
	v_add_f32_e32 v66, 1.0, v66
	v_add_f32_e32 v67, 1.0, v67
	v_add_f32_e32 v180, 1.0, v180
	v_add_f32_e32 v181, 1.0, v181
	v_rcp_f32_e32 v66, v66
	v_rcp_f32_e32 v67, v67
	v_rcp_f32_e32 v180, v180
	v_rcp_f32_e32 v181, v181
	v_mul_f32_e32 v66, v66, v178
	v_mul_f32_e32 v67, v67, v156
	v_mul_f32_e32 v180, v180, v179
	v_mul_f32_e32 v181, v181, v160
	v_mul_f32_e32 v66, v66, v180
	v_mul_f32_e32 v67, v67, v181
	v_lshlrev_b32_e32 v178, 16, v157
	v_and_b32_e32 v157, 0xffff0000, v157
	v_lshlrev_b32_e32 v179, 16, v161
	v_and_b32_e32 v161, 0xffff0000, v161
	v_mul_f32_e32 v68, 0xbfb8aa3b, v68
	v_mul_f32_e32 v69, 0xbfb8aa3b, v69
	v_mul_f32_e32 v180, 0xbfb8aa3b, v179
	v_mul_f32_e32 v181, 0xbfb8aa3b, v161
	v_exp_f32_e32 v68, v68
	v_exp_f32_e32 v69, v69
	v_exp_f32_e32 v180, v180
	v_exp_f32_e32 v181, v181
	v_add_f32_e32 v68, 1.0, v68
	v_add_f32_e32 v69, 1.0, v69
	v_add_f32_e32 v180, 1.0, v180
	v_add_f32_e32 v181, 1.0, v181
	v_rcp_f32_e32 v68, v68
	v_rcp_f32_e32 v69, v69
	v_rcp_f32_e32 v180, v180
	v_rcp_f32_e32 v181, v181
	v_mul_f32_e32 v68, v68, v178
	v_mul_f32_e32 v69, v69, v157
	v_mul_f32_e32 v180, v180, v179
	v_mul_f32_e32 v181, v181, v161
	v_mul_f32_e32 v68, v68, v180
	v_mul_f32_e32 v69, v69, v181
	v_cvt_pk_bf16_f32 v70, v70, v71
	v_cvt_pk_bf16_f32 v71, v72, v73
	v_cvt_pk_bf16_f32 v72, v66, v67
	v_cvt_pk_bf16_f32 v73, v68, v69
	global_store_dwordx4 v[146:147], v[70:73], off offset:256
	s_mov_b64 s[58:59], 0xa0000
	v_lshl_add_u64 v[146:147], v[146:147], 0, s[58:59]
	s_mov_b64 s[58:59], 0x8000
	v_lshl_add_u64 v[142:143], v[142:143], 0, s[58:59]
	s_mov_b64 s[58:59], 0x4000
	v_lshl_add_u64 v[144:145], v[144:145], 0, s[58:59]
	global_load_dwordx4 v[154:157], v[142:143], off
	global_load_dwordx4 v[158:161], v[144:145], off
	s_waitcnt vmcnt(6)
	v_lshlrev_b32_e32 v178, 16, v162
	v_and_b32_e32 v162, 0xffff0000, v162
	v_lshlrev_b32_e32 v179, 16, v166
	v_and_b32_e32 v166, 0xffff0000, v166
	v_mul_f32_e32 v62, 0xbfb8aa3b, v62
	v_mul_f32_e32 v63, 0xbfb8aa3b, v63
	v_mul_f32_e32 v180, 0xbfb8aa3b, v179
	v_mul_f32_e32 v181, 0xbfb8aa3b, v166
	v_exp_f32_e32 v62, v62
	v_exp_f32_e32 v63, v63
	v_exp_f32_e32 v180, v180
	v_exp_f32_e32 v181, v181
	v_add_f32_e32 v62, 1.0, v62
	v_add_f32_e32 v63, 1.0, v63
	v_add_f32_e32 v180, 1.0, v180
	v_add_f32_e32 v181, 1.0, v181
	v_rcp_f32_e32 v62, v62
	v_rcp_f32_e32 v63, v63
	v_rcp_f32_e32 v180, v180
	v_rcp_f32_e32 v181, v181
	v_mul_f32_e32 v62, v62, v178
	v_mul_f32_e32 v63, v63, v162
	v_mul_f32_e32 v180, v180, v179
	v_mul_f32_e32 v181, v181, v166
	v_mul_f32_e32 v62, v62, v180
	v_mul_f32_e32 v63, v63, v181
	v_lshlrev_b32_e32 v178, 16, v163
	v_and_b32_e32 v163, 0xffff0000, v163
	v_lshlrev_b32_e32 v179, 16, v167
	v_and_b32_e32 v167, 0xffff0000, v167
	v_mul_f32_e32 v64, 0xbfb8aa3b, v64
	v_mul_f32_e32 v65, 0xbfb8aa3b, v65
	v_mul_f32_e32 v180, 0xbfb8aa3b, v179
	v_mul_f32_e32 v181, 0xbfb8aa3b, v167
	v_exp_f32_e32 v64, v64
	v_exp_f32_e32 v65, v65
	v_exp_f32_e32 v180, v180
	v_exp_f32_e32 v181, v181
	v_add_f32_e32 v64, 1.0, v64
	v_add_f32_e32 v65, 1.0, v65
	v_add_f32_e32 v180, 1.0, v180
	v_add_f32_e32 v181, 1.0, v181
	v_rcp_f32_e32 v64, v64
	v_rcp_f32_e32 v65, v65
	v_rcp_f32_e32 v180, v180
	v_rcp_f32_e32 v181, v181
	v_mul_f32_e32 v64, v64, v178
	v_mul_f32_e32 v65, v65, v163
	v_mul_f32_e32 v180, v180, v179
	v_mul_f32_e32 v181, v181, v167
	v_mul_f32_e32 v64, v64, v180
	v_mul_f32_e32 v65, v65, v181
	v_lshlrev_b32_e32 v178, 16, v164
	v_and_b32_e32 v164, 0xffff0000, v164
	v_lshlrev_b32_e32 v179, 16, v168
	v_and_b32_e32 v168, 0xffff0000, v168
	v_mul_f32_e32 v58, 0xbfb8aa3b, v58
	v_mul_f32_e32 v59, 0xbfb8aa3b, v59
	v_mul_f32_e32 v180, 0xbfb8aa3b, v179
	v_mul_f32_e32 v181, 0xbfb8aa3b, v168
	v_exp_f32_e32 v58, v58
	v_exp_f32_e32 v59, v59
	v_exp_f32_e32 v180, v180
	v_exp_f32_e32 v181, v181
	v_add_f32_e32 v58, 1.0, v58
	v_add_f32_e32 v59, 1.0, v59
	v_add_f32_e32 v180, 1.0, v180
	v_add_f32_e32 v181, 1.0, v181
	v_rcp_f32_e32 v58, v58
	v_rcp_f32_e32 v59, v59
	v_rcp_f32_e32 v180, v180
	v_rcp_f32_e32 v181, v181
	v_mul_f32_e32 v58, v58, v178
	v_mul_f32_e32 v59, v59, v164
	v_mul_f32_e32 v180, v180, v179
	v_mul_f32_e32 v181, v181, v168
	v_mul_f32_e32 v58, v58, v180
	v_mul_f32_e32 v59, v59, v181
	v_lshlrev_b32_e32 v178, 16, v165
	v_and_b32_e32 v165, 0xffff0000, v165
	v_lshlrev_b32_e32 v179, 16, v169
	v_and_b32_e32 v169, 0xffff0000, v169
	v_mul_f32_e32 v60, 0xbfb8aa3b, v60
	v_mul_f32_e32 v61, 0xbfb8aa3b, v61
	v_mul_f32_e32 v180, 0xbfb8aa3b, v179
	v_mul_f32_e32 v181, 0xbfb8aa3b, v169
	v_exp_f32_e32 v60, v60
	v_exp_f32_e32 v61, v61
	v_exp_f32_e32 v180, v180
	v_exp_f32_e32 v181, v181
	v_add_f32_e32 v60, 1.0, v60
	v_add_f32_e32 v61, 1.0, v61
	v_add_f32_e32 v180, 1.0, v180
	v_add_f32_e32 v181, 1.0, v181
	v_rcp_f32_e32 v60, v60
	v_rcp_f32_e32 v61, v61
	v_rcp_f32_e32 v180, v180
	v_rcp_f32_e32 v181, v181
	v_mul_f32_e32 v60, v60, v178
	v_mul_f32_e32 v61, v61, v165
	v_mul_f32_e32 v180, v180, v179
	v_mul_f32_e32 v181, v181, v169
	v_mul_f32_e32 v60, v60, v180
	v_mul_f32_e32 v61, v61, v181
	v_cvt_pk_bf16_f32 v62, v62, v63
	v_cvt_pk_bf16_f32 v63, v64, v65
	v_cvt_pk_bf16_f32 v64, v58, v59
	v_cvt_pk_bf16_f32 v65, v60, v61
	global_store_dwordx4 v[146:147], v[62:65], off
	global_load_dwordx4 v[162:165], v[142:143], off offset:256
	global_load_dwordx4 v[166:169], v[144:145], off offset:256
	s_waitcnt vmcnt(6)
	v_lshlrev_b32_e32 v178, 16, v170
	v_and_b32_e32 v170, 0xffff0000, v170
	v_lshlrev_b32_e32 v179, 16, v174
	v_and_b32_e32 v174, 0xffff0000, v174
	v_mul_f32_e32 v54, 0xbfb8aa3b, v54
	v_mul_f32_e32 v55, 0xbfb8aa3b, v55
	v_mul_f32_e32 v180, 0xbfb8aa3b, v179
	v_mul_f32_e32 v181, 0xbfb8aa3b, v174
	v_exp_f32_e32 v54, v54
	v_exp_f32_e32 v55, v55
	v_exp_f32_e32 v180, v180
	v_exp_f32_e32 v181, v181
	v_add_f32_e32 v54, 1.0, v54
	v_add_f32_e32 v55, 1.0, v55
	v_add_f32_e32 v180, 1.0, v180
	v_add_f32_e32 v181, 1.0, v181
	v_rcp_f32_e32 v54, v54
	v_rcp_f32_e32 v55, v55
	v_rcp_f32_e32 v180, v180
	v_rcp_f32_e32 v181, v181
	v_mul_f32_e32 v54, v54, v178
	v_mul_f32_e32 v55, v55, v170
	v_mul_f32_e32 v180, v180, v179
	v_mul_f32_e32 v181, v181, v174
	v_mul_f32_e32 v54, v54, v180
	v_mul_f32_e32 v55, v55, v181
	v_lshlrev_b32_e32 v178, 16, v171
	v_and_b32_e32 v171, 0xffff0000, v171
	v_lshlrev_b32_e32 v179, 16, v175
	v_and_b32_e32 v175, 0xffff0000, v175
	v_mul_f32_e32 v56, 0xbfb8aa3b, v56
	v_mul_f32_e32 v57, 0xbfb8aa3b, v57
	v_mul_f32_e32 v180, 0xbfb8aa3b, v179
	v_mul_f32_e32 v181, 0xbfb8aa3b, v175
	v_exp_f32_e32 v56, v56
	v_exp_f32_e32 v57, v57
	v_exp_f32_e32 v180, v180
	v_exp_f32_e32 v181, v181
	v_add_f32_e32 v56, 1.0, v56
	v_add_f32_e32 v57, 1.0, v57
	v_add_f32_e32 v180, 1.0, v180
	v_add_f32_e32 v181, 1.0, v181
	v_rcp_f32_e32 v56, v56
	v_rcp_f32_e32 v57, v57
	v_rcp_f32_e32 v180, v180
	v_rcp_f32_e32 v181, v181
	v_mul_f32_e32 v56, v56, v178
	v_mul_f32_e32 v57, v57, v171
	v_mul_f32_e32 v180, v180, v179
	v_mul_f32_e32 v181, v181, v175
	v_mul_f32_e32 v56, v56, v180
	v_mul_f32_e32 v57, v57, v181
	v_lshlrev_b32_e32 v178, 16, v172
	v_and_b32_e32 v172, 0xffff0000, v172
	v_lshlrev_b32_e32 v179, 16, v176
	v_and_b32_e32 v176, 0xffff0000, v176
	v_mul_f32_e32 v50, 0xbfb8aa3b, v50
	v_mul_f32_e32 v51, 0xbfb8aa3b, v51
	v_mul_f32_e32 v180, 0xbfb8aa3b, v179
	v_mul_f32_e32 v181, 0xbfb8aa3b, v176
	v_exp_f32_e32 v50, v50
	v_exp_f32_e32 v51, v51
	v_exp_f32_e32 v180, v180
	v_exp_f32_e32 v181, v181
	v_add_f32_e32 v50, 1.0, v50
	v_add_f32_e32 v51, 1.0, v51
	v_add_f32_e32 v180, 1.0, v180
	v_add_f32_e32 v181, 1.0, v181
	v_rcp_f32_e32 v50, v50
	v_rcp_f32_e32 v51, v51
	v_rcp_f32_e32 v180, v180
	v_rcp_f32_e32 v181, v181
	v_mul_f32_e32 v50, v50, v178
	v_mul_f32_e32 v51, v51, v172
	v_mul_f32_e32 v180, v180, v179
	v_mul_f32_e32 v181, v181, v176
	v_mul_f32_e32 v50, v50, v180
	v_mul_f32_e32 v51, v51, v181
	v_lshlrev_b32_e32 v178, 16, v173
	v_and_b32_e32 v173, 0xffff0000, v173
	v_lshlrev_b32_e32 v179, 16, v177
	v_and_b32_e32 v177, 0xffff0000, v177
	v_mul_f32_e32 v52, 0xbfb8aa3b, v52
	v_mul_f32_e32 v53, 0xbfb8aa3b, v53
	v_mul_f32_e32 v180, 0xbfb8aa3b, v179
	v_mul_f32_e32 v181, 0xbfb8aa3b, v177
	v_exp_f32_e32 v52, v52
	v_exp_f32_e32 v53, v53
	v_exp_f32_e32 v180, v180
	v_exp_f32_e32 v181, v181
	v_add_f32_e32 v52, 1.0, v52
	v_add_f32_e32 v53, 1.0, v53
	v_add_f32_e32 v180, 1.0, v180
	v_add_f32_e32 v181, 1.0, v181
	v_rcp_f32_e32 v52, v52
	v_rcp_f32_e32 v53, v53
	v_rcp_f32_e32 v180, v180
	v_rcp_f32_e32 v181, v181
	v_mul_f32_e32 v52, v52, v178
	v_mul_f32_e32 v53, v53, v173
	v_mul_f32_e32 v180, v180, v179
	v_mul_f32_e32 v181, v181, v177
	v_mul_f32_e32 v52, v52, v180
	v_mul_f32_e32 v53, v53, v181
	v_cvt_pk_bf16_f32 v54, v54, v55
	v_cvt_pk_bf16_f32 v55, v56, v57
	v_cvt_pk_bf16_f32 v56, v50, v51
	v_cvt_pk_bf16_f32 v57, v52, v53
	global_store_dwordx4 v[146:147], v[54:57], off offset:256
	s_mov_b64 s[58:59], 0x20000
	v_lshl_add_u64 v[146:147], v[146:147], 0, s[58:59]
	s_mov_b64 s[58:59], 0x8000
	v_lshl_add_u64 v[142:143], v[142:143], 0, s[58:59]
	s_mov_b64 s[58:59], 0x4000
	v_lshl_add_u64 v[144:145], v[144:145], 0, s[58:59]
	global_load_dwordx4 v[170:173], v[142:143], off
	global_load_dwordx4 v[174:177], v[144:145], off
	s_waitcnt vmcnt(6)
	v_lshlrev_b32_e32 v178, 16, v154
	v_and_b32_e32 v154, 0xffff0000, v154
	v_lshlrev_b32_e32 v179, 16, v158
	v_and_b32_e32 v158, 0xffff0000, v158
	v_mul_f32_e32 v46, 0xbfb8aa3b, v46
	v_mul_f32_e32 v47, 0xbfb8aa3b, v47
	v_mul_f32_e32 v180, 0xbfb8aa3b, v179
	v_mul_f32_e32 v181, 0xbfb8aa3b, v158
	v_exp_f32_e32 v46, v46
	v_exp_f32_e32 v47, v47
	v_exp_f32_e32 v180, v180
	v_exp_f32_e32 v181, v181
	v_add_f32_e32 v46, 1.0, v46
	v_add_f32_e32 v47, 1.0, v47
	v_add_f32_e32 v180, 1.0, v180
	v_add_f32_e32 v181, 1.0, v181
	v_rcp_f32_e32 v46, v46
	v_rcp_f32_e32 v47, v47
	v_rcp_f32_e32 v180, v180
	v_rcp_f32_e32 v181, v181
	v_mul_f32_e32 v46, v46, v178
	v_mul_f32_e32 v47, v47, v154
	v_mul_f32_e32 v180, v180, v179
	v_mul_f32_e32 v181, v181, v158
	v_mul_f32_e32 v46, v46, v180
	v_mul_f32_e32 v47, v47, v181
	v_lshlrev_b32_e32 v178, 16, v155
	v_and_b32_e32 v155, 0xffff0000, v155
	v_lshlrev_b32_e32 v179, 16, v159
	v_and_b32_e32 v159, 0xffff0000, v159
	v_mul_f32_e32 v48, 0xbfb8aa3b, v48
	v_mul_f32_e32 v49, 0xbfb8aa3b, v49
	v_mul_f32_e32 v180, 0xbfb8aa3b, v179
	v_mul_f32_e32 v181, 0xbfb8aa3b, v159
	v_exp_f32_e32 v48, v48
	v_exp_f32_e32 v49, v49
	v_exp_f32_e32 v180, v180
	v_exp_f32_e32 v181, v181
	v_add_f32_e32 v48, 1.0, v48
	v_add_f32_e32 v49, 1.0, v49
	v_add_f32_e32 v180, 1.0, v180
	v_add_f32_e32 v181, 1.0, v181
	v_rcp_f32_e32 v48, v48
	v_rcp_f32_e32 v49, v49
	v_rcp_f32_e32 v180, v180
	v_rcp_f32_e32 v181, v181
	v_mul_f32_e32 v48, v48, v178
	v_mul_f32_e32 v49, v49, v155
	v_mul_f32_e32 v180, v180, v179
	v_mul_f32_e32 v181, v181, v159
	v_mul_f32_e32 v48, v48, v180
	v_mul_f32_e32 v49, v49, v181
	v_lshlrev_b32_e32 v178, 16, v156
	v_and_b32_e32 v156, 0xffff0000, v156
	v_lshlrev_b32_e32 v179, 16, v160
	v_and_b32_e32 v160, 0xffff0000, v160
	v_mul_f32_e32 v42, 0xbfb8aa3b, v42
	v_mul_f32_e32 v43, 0xbfb8aa3b, v43
	v_mul_f32_e32 v180, 0xbfb8aa3b, v179
	v_mul_f32_e32 v181, 0xbfb8aa3b, v160
	v_exp_f32_e32 v42, v42
	v_exp_f32_e32 v43, v43
	v_exp_f32_e32 v180, v180
	v_exp_f32_e32 v181, v181
	v_add_f32_e32 v42, 1.0, v42
	v_add_f32_e32 v43, 1.0, v43
	v_add_f32_e32 v180, 1.0, v180
	v_add_f32_e32 v181, 1.0, v181
	v_rcp_f32_e32 v42, v42
	v_rcp_f32_e32 v43, v43
	v_rcp_f32_e32 v180, v180
	v_rcp_f32_e32 v181, v181
	v_mul_f32_e32 v42, v42, v178
	v_mul_f32_e32 v43, v43, v156
	v_mul_f32_e32 v180, v180, v179
	v_mul_f32_e32 v181, v181, v160
	v_mul_f32_e32 v42, v42, v180
	v_mul_f32_e32 v43, v43, v181
	v_lshlrev_b32_e32 v178, 16, v157
	v_and_b32_e32 v157, 0xffff0000, v157
	v_lshlrev_b32_e32 v179, 16, v161
	v_and_b32_e32 v161, 0xffff0000, v161
	v_mul_f32_e32 v44, 0xbfb8aa3b, v44
	v_mul_f32_e32 v45, 0xbfb8aa3b, v45
	v_mul_f32_e32 v180, 0xbfb8aa3b, v179
	v_mul_f32_e32 v181, 0xbfb8aa3b, v161
	v_exp_f32_e32 v44, v44
	v_exp_f32_e32 v45, v45
	v_exp_f32_e32 v180, v180
	v_exp_f32_e32 v181, v181
	v_add_f32_e32 v44, 1.0, v44
	v_add_f32_e32 v45, 1.0, v45
	v_add_f32_e32 v180, 1.0, v180
	v_add_f32_e32 v181, 1.0, v181
	v_rcp_f32_e32 v44, v44
	v_rcp_f32_e32 v45, v45
	v_rcp_f32_e32 v180, v180
	v_rcp_f32_e32 v181, v181
	v_mul_f32_e32 v44, v44, v178
	v_mul_f32_e32 v45, v45, v157
	v_mul_f32_e32 v180, v180, v179
	v_mul_f32_e32 v181, v181, v161
	v_mul_f32_e32 v44, v44, v180
	v_mul_f32_e32 v45, v45, v181
	v_cvt_pk_bf16_f32 v46, v46, v47
	v_cvt_pk_bf16_f32 v47, v48, v49
	v_cvt_pk_bf16_f32 v48, v42, v43
	v_cvt_pk_bf16_f32 v49, v44, v45
	global_store_dwordx4 v[146:147], v[46:49], off
	global_load_dwordx4 v[154:157], v[142:143], off offset:256
	global_load_dwordx4 v[158:161], v[144:145], off offset:256
	s_waitcnt vmcnt(6)
	v_lshlrev_b32_e32 v178, 16, v162
	v_and_b32_e32 v162, 0xffff0000, v162
	v_lshlrev_b32_e32 v179, 16, v166
	v_and_b32_e32 v166, 0xffff0000, v166
	v_mul_f32_e32 v38, 0xbfb8aa3b, v38
	v_mul_f32_e32 v39, 0xbfb8aa3b, v39
	v_mul_f32_e32 v180, 0xbfb8aa3b, v179
	v_mul_f32_e32 v181, 0xbfb8aa3b, v166
	v_exp_f32_e32 v38, v38
	v_exp_f32_e32 v39, v39
	v_exp_f32_e32 v180, v180
	v_exp_f32_e32 v181, v181
	v_add_f32_e32 v38, 1.0, v38
	v_add_f32_e32 v39, 1.0, v39
	v_add_f32_e32 v180, 1.0, v180
	v_add_f32_e32 v181, 1.0, v181
	v_rcp_f32_e32 v38, v38
	v_rcp_f32_e32 v39, v39
	v_rcp_f32_e32 v180, v180
	v_rcp_f32_e32 v181, v181
	v_mul_f32_e32 v38, v38, v178
	v_mul_f32_e32 v39, v39, v162
	v_mul_f32_e32 v180, v180, v179
	v_mul_f32_e32 v181, v181, v166
	v_mul_f32_e32 v38, v38, v180
	v_mul_f32_e32 v39, v39, v181
	v_lshlrev_b32_e32 v178, 16, v163
	v_and_b32_e32 v163, 0xffff0000, v163
	v_lshlrev_b32_e32 v179, 16, v167
	v_and_b32_e32 v167, 0xffff0000, v167
	v_mul_f32_e32 v40, 0xbfb8aa3b, v40
	v_mul_f32_e32 v41, 0xbfb8aa3b, v41
	v_mul_f32_e32 v180, 0xbfb8aa3b, v179
	v_mul_f32_e32 v181, 0xbfb8aa3b, v167
	v_exp_f32_e32 v40, v40
	v_exp_f32_e32 v41, v41
	v_exp_f32_e32 v180, v180
	v_exp_f32_e32 v181, v181
	v_add_f32_e32 v40, 1.0, v40
	v_add_f32_e32 v41, 1.0, v41
	v_add_f32_e32 v180, 1.0, v180
	v_add_f32_e32 v181, 1.0, v181
	v_rcp_f32_e32 v40, v40
	v_rcp_f32_e32 v41, v41
	v_rcp_f32_e32 v180, v180
	v_rcp_f32_e32 v181, v181
	v_mul_f32_e32 v40, v40, v178
	v_mul_f32_e32 v41, v41, v163
	v_mul_f32_e32 v180, v180, v179
	v_mul_f32_e32 v181, v181, v167
	v_mul_f32_e32 v40, v40, v180
	v_mul_f32_e32 v41, v41, v181
	v_lshlrev_b32_e32 v178, 16, v164
	v_and_b32_e32 v164, 0xffff0000, v164
	v_lshlrev_b32_e32 v179, 16, v168
	v_and_b32_e32 v168, 0xffff0000, v168
	v_mul_f32_e32 v34, 0xbfb8aa3b, v34
	v_mul_f32_e32 v35, 0xbfb8aa3b, v35
	v_mul_f32_e32 v180, 0xbfb8aa3b, v179
	v_mul_f32_e32 v181, 0xbfb8aa3b, v168
	v_exp_f32_e32 v34, v34
	v_exp_f32_e32 v35, v35
	v_exp_f32_e32 v180, v180
	v_exp_f32_e32 v181, v181
	v_add_f32_e32 v34, 1.0, v34
	v_add_f32_e32 v35, 1.0, v35
	v_add_f32_e32 v180, 1.0, v180
	v_add_f32_e32 v181, 1.0, v181
	v_rcp_f32_e32 v34, v34
	v_rcp_f32_e32 v35, v35
	v_rcp_f32_e32 v180, v180
	v_rcp_f32_e32 v181, v181
	v_mul_f32_e32 v34, v34, v178
	v_mul_f32_e32 v35, v35, v164
	v_mul_f32_e32 v180, v180, v179
	v_mul_f32_e32 v181, v181, v168
	v_mul_f32_e32 v34, v34, v180
	v_mul_f32_e32 v35, v35, v181
	v_lshlrev_b32_e32 v178, 16, v165
	v_and_b32_e32 v165, 0xffff0000, v165
	v_lshlrev_b32_e32 v179, 16, v169
	v_and_b32_e32 v169, 0xffff0000, v169
	v_mul_f32_e32 v36, 0xbfb8aa3b, v36
	v_mul_f32_e32 v37, 0xbfb8aa3b, v37
	v_mul_f32_e32 v180, 0xbfb8aa3b, v179
	v_mul_f32_e32 v181, 0xbfb8aa3b, v169
	v_exp_f32_e32 v36, v36
	v_exp_f32_e32 v37, v37
	v_exp_f32_e32 v180, v180
	v_exp_f32_e32 v181, v181
	v_add_f32_e32 v36, 1.0, v36
	v_add_f32_e32 v37, 1.0, v37
	v_add_f32_e32 v180, 1.0, v180
	v_add_f32_e32 v181, 1.0, v181
	v_rcp_f32_e32 v36, v36
	v_rcp_f32_e32 v37, v37
	v_rcp_f32_e32 v180, v180
	v_rcp_f32_e32 v181, v181
	v_mul_f32_e32 v36, v36, v178
	v_mul_f32_e32 v37, v37, v165
	v_mul_f32_e32 v180, v180, v179
	v_mul_f32_e32 v181, v181, v169
	v_mul_f32_e32 v36, v36, v180
	v_mul_f32_e32 v37, v37, v181
	v_cvt_pk_bf16_f32 v38, v38, v39
	v_cvt_pk_bf16_f32 v39, v40, v41
	v_cvt_pk_bf16_f32 v40, v34, v35
	v_cvt_pk_bf16_f32 v41, v36, v37
	global_store_dwordx4 v[146:147], v[38:41], off offset:256
	s_mov_b64 s[58:59], 0x20000
	v_lshl_add_u64 v[146:147], v[146:147], 0, s[58:59]
	s_mov_b64 s[58:59], 0x8000
	v_lshl_add_u64 v[142:143], v[142:143], 0, s[58:59]
	s_mov_b64 s[58:59], 0x4000
	v_lshl_add_u64 v[144:145], v[144:145], 0, s[58:59]
	global_load_dwordx4 v[162:165], v[142:143], off
	global_load_dwordx4 v[166:169], v[144:145], off
	s_waitcnt vmcnt(6)
	v_lshlrev_b32_e32 v178, 16, v170
	v_and_b32_e32 v170, 0xffff0000, v170
	v_lshlrev_b32_e32 v179, 16, v174
	v_and_b32_e32 v174, 0xffff0000, v174
	v_mul_f32_e32 v30, 0xbfb8aa3b, v30
	v_mul_f32_e32 v31, 0xbfb8aa3b, v31
	v_mul_f32_e32 v180, 0xbfb8aa3b, v179
	v_mul_f32_e32 v181, 0xbfb8aa3b, v174
	v_exp_f32_e32 v30, v30
	v_exp_f32_e32 v31, v31
	v_exp_f32_e32 v180, v180
	v_exp_f32_e32 v181, v181
	v_add_f32_e32 v30, 1.0, v30
	v_add_f32_e32 v31, 1.0, v31
	v_add_f32_e32 v180, 1.0, v180
	v_add_f32_e32 v181, 1.0, v181
	v_rcp_f32_e32 v30, v30
	v_rcp_f32_e32 v31, v31
	v_rcp_f32_e32 v180, v180
	v_rcp_f32_e32 v181, v181
	v_mul_f32_e32 v30, v30, v178
	v_mul_f32_e32 v31, v31, v170
	v_mul_f32_e32 v180, v180, v179
	v_mul_f32_e32 v181, v181, v174
	v_mul_f32_e32 v30, v30, v180
	v_mul_f32_e32 v31, v31, v181
	v_lshlrev_b32_e32 v178, 16, v171
	v_and_b32_e32 v171, 0xffff0000, v171
	v_lshlrev_b32_e32 v179, 16, v175
	v_and_b32_e32 v175, 0xffff0000, v175
	v_mul_f32_e32 v32, 0xbfb8aa3b, v32
	v_mul_f32_e32 v33, 0xbfb8aa3b, v33
	v_mul_f32_e32 v180, 0xbfb8aa3b, v179
	v_mul_f32_e32 v181, 0xbfb8aa3b, v175
	v_exp_f32_e32 v32, v32
	v_exp_f32_e32 v33, v33
	v_exp_f32_e32 v180, v180
	v_exp_f32_e32 v181, v181
	v_add_f32_e32 v32, 1.0, v32
	v_add_f32_e32 v33, 1.0, v33
	v_add_f32_e32 v180, 1.0, v180
	v_add_f32_e32 v181, 1.0, v181
	v_rcp_f32_e32 v32, v32
	v_rcp_f32_e32 v33, v33
	v_rcp_f32_e32 v180, v180
	v_rcp_f32_e32 v181, v181
	v_mul_f32_e32 v32, v32, v178
	v_mul_f32_e32 v33, v33, v171
	v_mul_f32_e32 v180, v180, v179
	v_mul_f32_e32 v181, v181, v175
	v_mul_f32_e32 v32, v32, v180
	v_mul_f32_e32 v33, v33, v181
	v_lshlrev_b32_e32 v178, 16, v172
	v_and_b32_e32 v172, 0xffff0000, v172
	v_lshlrev_b32_e32 v179, 16, v176
	v_and_b32_e32 v176, 0xffff0000, v176
	v_mul_f32_e32 v26, 0xbfb8aa3b, v26
	v_mul_f32_e32 v27, 0xbfb8aa3b, v27
	v_mul_f32_e32 v180, 0xbfb8aa3b, v179
	v_mul_f32_e32 v181, 0xbfb8aa3b, v176
	v_exp_f32_e32 v26, v26
	v_exp_f32_e32 v27, v27
	v_exp_f32_e32 v180, v180
	v_exp_f32_e32 v181, v181
	v_add_f32_e32 v26, 1.0, v26
	v_add_f32_e32 v27, 1.0, v27
	v_add_f32_e32 v180, 1.0, v180
	v_add_f32_e32 v181, 1.0, v181
	v_rcp_f32_e32 v26, v26
	v_rcp_f32_e32 v27, v27
	v_rcp_f32_e32 v180, v180
	v_rcp_f32_e32 v181, v181
	v_mul_f32_e32 v26, v26, v178
	v_mul_f32_e32 v27, v27, v172
	v_mul_f32_e32 v180, v180, v179
	v_mul_f32_e32 v181, v181, v176
	v_mul_f32_e32 v26, v26, v180
	v_mul_f32_e32 v27, v27, v181
	v_lshlrev_b32_e32 v178, 16, v173
	v_and_b32_e32 v173, 0xffff0000, v173
	v_lshlrev_b32_e32 v179, 16, v177
	v_and_b32_e32 v177, 0xffff0000, v177
	v_mul_f32_e32 v28, 0xbfb8aa3b, v28
	v_mul_f32_e32 v29, 0xbfb8aa3b, v29
	v_mul_f32_e32 v180, 0xbfb8aa3b, v179
	v_mul_f32_e32 v181, 0xbfb8aa3b, v177
	v_exp_f32_e32 v28, v28
	v_exp_f32_e32 v29, v29
	v_exp_f32_e32 v180, v180
	v_exp_f32_e32 v181, v181
	v_add_f32_e32 v28, 1.0, v28
	v_add_f32_e32 v29, 1.0, v29
	v_add_f32_e32 v180, 1.0, v180
	v_add_f32_e32 v181, 1.0, v181
	v_rcp_f32_e32 v28, v28
	v_rcp_f32_e32 v29, v29
	v_rcp_f32_e32 v180, v180
	v_rcp_f32_e32 v181, v181
	v_mul_f32_e32 v28, v28, v178
	v_mul_f32_e32 v29, v29, v173
	v_mul_f32_e32 v180, v180, v179
	v_mul_f32_e32 v181, v181, v177
	v_mul_f32_e32 v28, v28, v180
	v_mul_f32_e32 v29, v29, v181
	v_cvt_pk_bf16_f32 v30, v30, v31
	v_cvt_pk_bf16_f32 v31, v32, v33
	v_cvt_pk_bf16_f32 v32, v26, v27
	v_cvt_pk_bf16_f32 v33, v28, v29
	global_store_dwordx4 v[146:147], v[30:33], off
	global_load_dwordx4 v[170:173], v[142:143], off offset:256
	global_load_dwordx4 v[174:177], v[144:145], off offset:256
	s_waitcnt vmcnt(6)
	v_lshlrev_b32_e32 v178, 16, v154
	v_and_b32_e32 v154, 0xffff0000, v154
	v_lshlrev_b32_e32 v179, 16, v158
	v_and_b32_e32 v158, 0xffff0000, v158
	v_mul_f32_e32 v22, 0xbfb8aa3b, v22
	v_mul_f32_e32 v23, 0xbfb8aa3b, v23
	v_mul_f32_e32 v180, 0xbfb8aa3b, v179
	v_mul_f32_e32 v181, 0xbfb8aa3b, v158
	v_exp_f32_e32 v22, v22
	v_exp_f32_e32 v23, v23
	v_exp_f32_e32 v180, v180
	v_exp_f32_e32 v181, v181
	v_add_f32_e32 v22, 1.0, v22
	v_add_f32_e32 v23, 1.0, v23
	v_add_f32_e32 v180, 1.0, v180
	v_add_f32_e32 v181, 1.0, v181
	v_rcp_f32_e32 v22, v22
	v_rcp_f32_e32 v23, v23
	v_rcp_f32_e32 v180, v180
	v_rcp_f32_e32 v181, v181
	v_mul_f32_e32 v22, v22, v178
	v_mul_f32_e32 v23, v23, v154
	v_mul_f32_e32 v180, v180, v179
	v_mul_f32_e32 v181, v181, v158
	v_mul_f32_e32 v22, v22, v180
	v_mul_f32_e32 v23, v23, v181
	v_lshlrev_b32_e32 v178, 16, v155
	v_and_b32_e32 v155, 0xffff0000, v155
	v_lshlrev_b32_e32 v179, 16, v159
	v_and_b32_e32 v159, 0xffff0000, v159
	v_mul_f32_e32 v24, 0xbfb8aa3b, v24
	v_mul_f32_e32 v25, 0xbfb8aa3b, v25
	v_mul_f32_e32 v180, 0xbfb8aa3b, v179
	v_mul_f32_e32 v181, 0xbfb8aa3b, v159
	v_exp_f32_e32 v24, v24
	v_exp_f32_e32 v25, v25
	v_exp_f32_e32 v180, v180
	v_exp_f32_e32 v181, v181
	v_add_f32_e32 v24, 1.0, v24
	v_add_f32_e32 v25, 1.0, v25
	v_add_f32_e32 v180, 1.0, v180
	v_add_f32_e32 v181, 1.0, v181
	v_rcp_f32_e32 v24, v24
	v_rcp_f32_e32 v25, v25
	v_rcp_f32_e32 v180, v180
	v_rcp_f32_e32 v181, v181
	v_mul_f32_e32 v24, v24, v178
	v_mul_f32_e32 v25, v25, v155
	v_mul_f32_e32 v180, v180, v179
	v_mul_f32_e32 v181, v181, v159
	v_mul_f32_e32 v24, v24, v180
	v_mul_f32_e32 v25, v25, v181
	v_lshlrev_b32_e32 v178, 16, v156
	v_and_b32_e32 v156, 0xffff0000, v156
	v_lshlrev_b32_e32 v179, 16, v160
	v_and_b32_e32 v160, 0xffff0000, v160
	v_mul_f32_e32 v18, 0xbfb8aa3b, v18
	v_mul_f32_e32 v19, 0xbfb8aa3b, v19
	v_mul_f32_e32 v180, 0xbfb8aa3b, v179
	v_mul_f32_e32 v181, 0xbfb8aa3b, v160
	v_exp_f32_e32 v18, v18
	v_exp_f32_e32 v19, v19
	v_exp_f32_e32 v180, v180
	v_exp_f32_e32 v181, v181
	v_add_f32_e32 v18, 1.0, v18
	v_add_f32_e32 v19, 1.0, v19
	v_add_f32_e32 v180, 1.0, v180
	v_add_f32_e32 v181, 1.0, v181
	v_rcp_f32_e32 v18, v18
	v_rcp_f32_e32 v19, v19
	v_rcp_f32_e32 v180, v180
	v_rcp_f32_e32 v181, v181
	v_mul_f32_e32 v18, v18, v178
	v_mul_f32_e32 v19, v19, v156
	v_mul_f32_e32 v180, v180, v179
	v_mul_f32_e32 v181, v181, v160
	v_mul_f32_e32 v18, v18, v180
	v_mul_f32_e32 v19, v19, v181
	v_lshlrev_b32_e32 v178, 16, v157
	v_and_b32_e32 v157, 0xffff0000, v157
	v_lshlrev_b32_e32 v179, 16, v161
	v_and_b32_e32 v161, 0xffff0000, v161
	v_mul_f32_e32 v20, 0xbfb8aa3b, v20
	v_mul_f32_e32 v21, 0xbfb8aa3b, v21
	v_mul_f32_e32 v180, 0xbfb8aa3b, v179
	v_mul_f32_e32 v181, 0xbfb8aa3b, v161
	v_exp_f32_e32 v20, v20
	v_exp_f32_e32 v21, v21
	v_exp_f32_e32 v180, v180
	v_exp_f32_e32 v181, v181
	v_add_f32_e32 v20, 1.0, v20
	v_add_f32_e32 v21, 1.0, v21
	v_add_f32_e32 v180, 1.0, v180
	v_add_f32_e32 v181, 1.0, v181
	v_rcp_f32_e32 v20, v20
	v_rcp_f32_e32 v21, v21
	v_rcp_f32_e32 v180, v180
	v_rcp_f32_e32 v181, v181
	v_mul_f32_e32 v20, v20, v178
	v_mul_f32_e32 v21, v21, v157
	v_mul_f32_e32 v180, v180, v179
	v_mul_f32_e32 v181, v181, v161
	v_mul_f32_e32 v20, v20, v180
	v_mul_f32_e32 v21, v21, v181
	v_cvt_pk_bf16_f32 v22, v22, v23
	v_cvt_pk_bf16_f32 v23, v24, v25
	v_cvt_pk_bf16_f32 v24, v18, v19
	v_cvt_pk_bf16_f32 v25, v20, v21
	global_store_dwordx4 v[146:147], v[22:25], off offset:256
	s_mov_b64 s[58:59], 0x20000
	v_lshl_add_u64 v[146:147], v[146:147], 0, s[58:59]
	s_waitcnt vmcnt(4)
	v_lshlrev_b32_e32 v178, 16, v162
	v_and_b32_e32 v162, 0xffff0000, v162
	v_lshlrev_b32_e32 v179, 16, v166
	v_and_b32_e32 v166, 0xffff0000, v166
	v_mul_f32_e32 v14, 0xbfb8aa3b, v14
	v_mul_f32_e32 v15, 0xbfb8aa3b, v15
	v_mul_f32_e32 v180, 0xbfb8aa3b, v179
	v_mul_f32_e32 v181, 0xbfb8aa3b, v166
	v_exp_f32_e32 v14, v14
	v_exp_f32_e32 v15, v15
	v_exp_f32_e32 v180, v180
	v_exp_f32_e32 v181, v181
	v_add_f32_e32 v14, 1.0, v14
	v_add_f32_e32 v15, 1.0, v15
	v_add_f32_e32 v180, 1.0, v180
	v_add_f32_e32 v181, 1.0, v181
	v_rcp_f32_e32 v14, v14
	v_rcp_f32_e32 v15, v15
	v_rcp_f32_e32 v180, v180
	v_rcp_f32_e32 v181, v181
	v_mul_f32_e32 v14, v14, v178
	v_mul_f32_e32 v15, v15, v162
	v_mul_f32_e32 v180, v180, v179
	v_mul_f32_e32 v181, v181, v166
	v_mul_f32_e32 v14, v14, v180
	v_mul_f32_e32 v15, v15, v181
	v_lshlrev_b32_e32 v178, 16, v163
	v_and_b32_e32 v163, 0xffff0000, v163
	v_lshlrev_b32_e32 v179, 16, v167
	v_and_b32_e32 v167, 0xffff0000, v167
	v_mul_f32_e32 v16, 0xbfb8aa3b, v16
	v_mul_f32_e32 v17, 0xbfb8aa3b, v17
	v_mul_f32_e32 v180, 0xbfb8aa3b, v179
	v_mul_f32_e32 v181, 0xbfb8aa3b, v167
	v_exp_f32_e32 v16, v16
	v_exp_f32_e32 v17, v17
	v_exp_f32_e32 v180, v180
	v_exp_f32_e32 v181, v181
	v_add_f32_e32 v16, 1.0, v16
	v_add_f32_e32 v17, 1.0, v17
	v_add_f32_e32 v180, 1.0, v180
	v_add_f32_e32 v181, 1.0, v181
	v_rcp_f32_e32 v16, v16
	v_rcp_f32_e32 v17, v17
	v_rcp_f32_e32 v180, v180
	v_rcp_f32_e32 v181, v181
	v_mul_f32_e32 v16, v16, v178
	v_mul_f32_e32 v17, v17, v163
	v_mul_f32_e32 v180, v180, v179
	v_mul_f32_e32 v181, v181, v167
	v_mul_f32_e32 v16, v16, v180
	v_mul_f32_e32 v17, v17, v181
	v_lshlrev_b32_e32 v178, 16, v164
	v_and_b32_e32 v164, 0xffff0000, v164
	v_lshlrev_b32_e32 v179, 16, v168
	v_and_b32_e32 v168, 0xffff0000, v168
	v_mul_f32_e32 v10, 0xbfb8aa3b, v10
	v_mul_f32_e32 v11, 0xbfb8aa3b, v11
	v_mul_f32_e32 v180, 0xbfb8aa3b, v179
	v_mul_f32_e32 v181, 0xbfb8aa3b, v168
	v_exp_f32_e32 v10, v10
	v_exp_f32_e32 v11, v11
	v_exp_f32_e32 v180, v180
	v_exp_f32_e32 v181, v181
	v_add_f32_e32 v10, 1.0, v10
	v_add_f32_e32 v11, 1.0, v11
	v_add_f32_e32 v180, 1.0, v180
	v_add_f32_e32 v181, 1.0, v181
	v_rcp_f32_e32 v10, v10
	v_rcp_f32_e32 v11, v11
	v_rcp_f32_e32 v180, v180
	v_rcp_f32_e32 v181, v181
	v_mul_f32_e32 v10, v10, v178
	v_mul_f32_e32 v11, v11, v164
	v_mul_f32_e32 v180, v180, v179
	v_mul_f32_e32 v181, v181, v168
	v_mul_f32_e32 v10, v10, v180
	v_mul_f32_e32 v11, v11, v181
	v_lshlrev_b32_e32 v178, 16, v165
	v_and_b32_e32 v165, 0xffff0000, v165
	v_lshlrev_b32_e32 v179, 16, v169
	v_and_b32_e32 v169, 0xffff0000, v169
	v_mul_f32_e32 v12, 0xbfb8aa3b, v12
	v_mul_f32_e32 v13, 0xbfb8aa3b, v13
	v_mul_f32_e32 v180, 0xbfb8aa3b, v179
	v_mul_f32_e32 v181, 0xbfb8aa3b, v169
	v_exp_f32_e32 v12, v12
	v_exp_f32_e32 v13, v13
	v_exp_f32_e32 v180, v180
	v_exp_f32_e32 v181, v181
	v_add_f32_e32 v12, 1.0, v12
	v_add_f32_e32 v13, 1.0, v13
	v_add_f32_e32 v180, 1.0, v180
	v_add_f32_e32 v181, 1.0, v181
	v_rcp_f32_e32 v12, v12
	v_rcp_f32_e32 v13, v13
	v_rcp_f32_e32 v180, v180
	v_rcp_f32_e32 v181, v181
	v_mul_f32_e32 v12, v12, v178
	v_mul_f32_e32 v13, v13, v165
	v_mul_f32_e32 v180, v180, v179
	v_mul_f32_e32 v181, v181, v169
	v_mul_f32_e32 v12, v12, v180
	v_mul_f32_e32 v13, v13, v181
	v_cvt_pk_bf16_f32 v14, v14, v15
	v_cvt_pk_bf16_f32 v15, v16, v17
	v_cvt_pk_bf16_f32 v16, v10, v11
	v_cvt_pk_bf16_f32 v17, v12, v13
	global_store_dwordx4 v[146:147], v[14:17], off
	s_waitcnt vmcnt(2)
	v_lshlrev_b32_e32 v178, 16, v170
	v_and_b32_e32 v170, 0xffff0000, v170
	v_lshlrev_b32_e32 v179, 16, v174
	v_and_b32_e32 v174, 0xffff0000, v174
	v_mul_f32_e32 v6, 0xbfb8aa3b, v6
	v_mul_f32_e32 v7, 0xbfb8aa3b, v7
	v_mul_f32_e32 v180, 0xbfb8aa3b, v179
	v_mul_f32_e32 v181, 0xbfb8aa3b, v174
	v_exp_f32_e32 v6, v6
	v_exp_f32_e32 v7, v7
	v_exp_f32_e32 v180, v180
	v_exp_f32_e32 v181, v181
	v_add_f32_e32 v6, 1.0, v6
	v_add_f32_e32 v7, 1.0, v7
	v_add_f32_e32 v180, 1.0, v180
	v_add_f32_e32 v181, 1.0, v181
	v_rcp_f32_e32 v6, v6
	v_rcp_f32_e32 v7, v7
	v_rcp_f32_e32 v180, v180
	v_rcp_f32_e32 v181, v181
	v_mul_f32_e32 v6, v6, v178
	v_mul_f32_e32 v7, v7, v170
	v_mul_f32_e32 v180, v180, v179
	v_mul_f32_e32 v181, v181, v174
	v_mul_f32_e32 v6, v6, v180
	v_mul_f32_e32 v7, v7, v181
	v_lshlrev_b32_e32 v178, 16, v171
	v_and_b32_e32 v171, 0xffff0000, v171
	v_lshlrev_b32_e32 v179, 16, v175
	v_and_b32_e32 v175, 0xffff0000, v175
	v_mul_f32_e32 v8, 0xbfb8aa3b, v8
	v_mul_f32_e32 v9, 0xbfb8aa3b, v9
	v_mul_f32_e32 v180, 0xbfb8aa3b, v179
	v_mul_f32_e32 v181, 0xbfb8aa3b, v175
	v_exp_f32_e32 v8, v8
	v_exp_f32_e32 v9, v9
	v_exp_f32_e32 v180, v180
	v_exp_f32_e32 v181, v181
	v_add_f32_e32 v8, 1.0, v8
	v_add_f32_e32 v9, 1.0, v9
	v_add_f32_e32 v180, 1.0, v180
	v_add_f32_e32 v181, 1.0, v181
	v_rcp_f32_e32 v8, v8
	v_rcp_f32_e32 v9, v9
	v_rcp_f32_e32 v180, v180
	v_rcp_f32_e32 v181, v181
	v_mul_f32_e32 v8, v8, v178
	v_mul_f32_e32 v9, v9, v171
	v_mul_f32_e32 v180, v180, v179
	v_mul_f32_e32 v181, v181, v175
	v_mul_f32_e32 v8, v8, v180
	v_mul_f32_e32 v9, v9, v181
	v_lshlrev_b32_e32 v178, 16, v172
	v_and_b32_e32 v172, 0xffff0000, v172
	v_lshlrev_b32_e32 v179, 16, v176
	v_and_b32_e32 v176, 0xffff0000, v176
	v_mul_f32_e32 v2, 0xbfb8aa3b, v2
	v_mul_f32_e32 v3, 0xbfb8aa3b, v3
	v_mul_f32_e32 v180, 0xbfb8aa3b, v179
	v_mul_f32_e32 v181, 0xbfb8aa3b, v176
	v_exp_f32_e32 v2, v2
	v_exp_f32_e32 v3, v3
	v_exp_f32_e32 v180, v180
	v_exp_f32_e32 v181, v181
	v_add_f32_e32 v2, 1.0, v2
	v_add_f32_e32 v3, 1.0, v3
	v_add_f32_e32 v180, 1.0, v180
	v_add_f32_e32 v181, 1.0, v181
	v_rcp_f32_e32 v2, v2
	v_rcp_f32_e32 v3, v3
	v_rcp_f32_e32 v180, v180
	v_rcp_f32_e32 v181, v181
	v_mul_f32_e32 v2, v2, v178
	v_mul_f32_e32 v3, v3, v172
	v_mul_f32_e32 v180, v180, v179
	v_mul_f32_e32 v181, v181, v176
	v_mul_f32_e32 v2, v2, v180
	v_mul_f32_e32 v3, v3, v181
	v_lshlrev_b32_e32 v178, 16, v173
	v_and_b32_e32 v173, 0xffff0000, v173
	v_lshlrev_b32_e32 v179, 16, v177
	v_and_b32_e32 v177, 0xffff0000, v177
	v_mul_f32_e32 v4, 0xbfb8aa3b, v4
	v_mul_f32_e32 v5, 0xbfb8aa3b, v5
	v_mul_f32_e32 v180, 0xbfb8aa3b, v179
	v_mul_f32_e32 v181, 0xbfb8aa3b, v177
	v_exp_f32_e32 v4, v4
	v_exp_f32_e32 v5, v5
	v_exp_f32_e32 v180, v180
	v_exp_f32_e32 v181, v181
	v_add_f32_e32 v4, 1.0, v4
	v_add_f32_e32 v5, 1.0, v5
	v_add_f32_e32 v180, 1.0, v180
	v_add_f32_e32 v181, 1.0, v181
	v_rcp_f32_e32 v4, v4
	v_rcp_f32_e32 v5, v5
	v_rcp_f32_e32 v180, v180
	v_rcp_f32_e32 v181, v181
	v_mul_f32_e32 v4, v4, v178
	v_mul_f32_e32 v5, v5, v173
	v_mul_f32_e32 v180, v180, v179
	v_mul_f32_e32 v181, v181, v177
	v_mul_f32_e32 v4, v4, v180
	v_mul_f32_e32 v5, v5, v181
	v_cvt_pk_bf16_f32 v6, v6, v7
	v_cvt_pk_bf16_f32 v7, v8, v9
	v_cvt_pk_bf16_f32 v8, v2, v3
	v_cvt_pk_bf16_f32 v9, v4, v5
	global_store_dwordx4 v[146:147], v[6:9], off offset:256
	s_andn2_b64 vcc, exec, s[38:39]
	s_mov_b64 s[4:5], -1
	s_cbranch_vccnz .LBB0_686
	s_andn2_b64 vcc, exec, s[42:43]
	s_cbranch_vccnz .LBB0_685
	s_barrier
	s_branch .LBB0_685
.LBB0_698:
	v_readlane_b32 s60, v255, 0
	s_waitcnt vmcnt(0)
	v_readlane_b32 s61, v255, 1
	v_readlane_b32 s70, v254, 62
	v_readlane_b32 s60, v255, 6
	v_readlane_b32 s71, v254, 63
	v_readlane_b32 s62, v255, 2
	v_readlane_b32 s63, v255, 3
	v_readlane_b32 s61, v255, 7
	s_barrier
